# GEMM K-loops: counter/pointer updates and exit compare moved under the last MFMA block, ahead of the loop-closing barrier (loop-edge edit)
# baseline (speedup 1.0000x reference)
.LBB0_395:
	ds_read_b128 v[152:155], v149
	ds_read_b128 v[156:159], v149 offset:1024
	ds_read_b128 v[160:163], v149 offset:2048
	ds_read_b128 v[164:167], v149 offset:3072
	ds_read_b128 v[168:171], v150
	ds_read_b128 v[172:175], v150 offset:1024
	ds_read_b128 v[176:179], v150 offset:2048
	ds_read_b128 v[180:183], v150 offset:3072
	s_add_u32 s24, s22, 0xfffc0080
	s_addc_u32 s25, s23, -1
	s_cmp_eq_u32 s45, 12
	s_cselect_b32 s27, s17, s25
	s_cselect_b32 s26, s41, s24
	s_cselect_b32 s25, s15, s44
	s_cselect_b32 s24, s42, s43
	v_lshl_add_u64 v[216:217], s[22:23], 0, v[138:139]
	s_add_i32 m0, s13, 0xc000
	ds_read_b128 v[184:187], v151
	ds_read_b128 v[188:191], v151 offset:1024
	ds_read_b128 v[192:195], v151 offset:2048
	ds_read_b128 v[196:199], v151 offset:3072
	ds_read_b128 v[200:203], v151 offset:4096
	ds_read_b128 v[204:207], v151 offset:5120
	ds_read_b128 v[208:211], v151 offset:6144
	ds_read_b128 v[212:215], v151 offset:7168
	global_load_lds_dwordx4 v[216:217], off
	v_lshl_add_u64 v[216:217], s[22:23], 0, v[140:141]
	s_add_i32 m0, s13, 0xe000
	s_nop 0
	global_load_lds_dwordx4 v[216:217], off
	s_waitcnt vmcnt(8)
	s_waitcnt lgkmcnt(0)
	s_barrier
	s_setprio 1
	s_waitcnt lgkmcnt(0)
	v_mfma_f32_16x16x32_bf16 v[126:129], v[152:155], v[184:187], v[126:129]
	v_mfma_f32_16x16x32_bf16 v[122:125], v[160:163], v[184:187], v[122:125]
	v_mfma_f32_16x16x32_bf16 v[118:121], v[152:155], v[192:195], v[118:121]
	v_mfma_f32_16x16x32_bf16 v[114:117], v[160:163], v[192:195], v[114:117]
	v_mfma_f32_16x16x32_bf16 v[102:105], v[152:155], v[200:203], v[102:105]
	v_mfma_f32_16x16x32_bf16 v[98:101], v[160:163], v[200:203], v[98:101]
	v_mfma_f32_16x16x32_bf16 v[86:89], v[152:155], v[208:211], v[86:89]
	v_mfma_f32_16x16x32_bf16 v[82:85], v[160:163], v[208:211], v[82:85]
	v_mfma_f32_16x16x32_bf16 v[126:129], v[156:159], v[188:191], v[126:129]
	v_mfma_f32_16x16x32_bf16 v[122:125], v[164:167], v[188:191], v[122:125]
	v_mfma_f32_16x16x32_bf16 v[118:121], v[156:159], v[196:199], v[118:121]
	v_mfma_f32_16x16x32_bf16 v[114:117], v[164:167], v[196:199], v[114:117]
	v_mfma_f32_16x16x32_bf16 v[102:105], v[156:159], v[204:207], v[102:105]
	v_mfma_f32_16x16x32_bf16 v[98:101], v[164:167], v[204:207], v[98:101]
	v_mfma_f32_16x16x32_bf16 v[86:89], v[156:159], v[212:215], v[86:89]
	v_mfma_f32_16x16x32_bf16 v[82:85], v[164:167], v[212:215], v[82:85]
	s_setprio 0
	s_setprio 1
	v_mfma_f32_16x16x32_bf16 v[110:113], v[168:171], v[184:187], v[110:113]
	v_mfma_f32_16x16x32_bf16 v[106:109], v[176:179], v[184:187], v[106:109]
	v_mfma_f32_16x16x32_bf16 v[94:97], v[168:171], v[192:195], v[94:97]
	v_mfma_f32_16x16x32_bf16 v[90:93], v[176:179], v[192:195], v[90:93]
	v_mfma_f32_16x16x32_bf16 v[78:81], v[168:171], v[200:203], v[78:81]
	v_mfma_f32_16x16x32_bf16 v[74:77], v[176:179], v[200:203], v[74:77]
	v_mfma_f32_16x16x32_bf16 v[70:73], v[168:171], v[208:211], v[70:73]
	v_mfma_f32_16x16x32_bf16 v[66:69], v[176:179], v[208:211], v[66:69]
	v_mfma_f32_16x16x32_bf16 v[110:113], v[172:175], v[188:191], v[110:113]
	v_mfma_f32_16x16x32_bf16 v[106:109], v[180:183], v[188:191], v[106:109]
	v_mfma_f32_16x16x32_bf16 v[94:97], v[172:175], v[196:199], v[94:97]
	v_mfma_f32_16x16x32_bf16 v[90:93], v[180:183], v[196:199], v[90:93]
	v_mfma_f32_16x16x32_bf16 v[78:81], v[172:175], v[204:207], v[78:81]
	v_mfma_f32_16x16x32_bf16 v[74:77], v[180:183], v[204:207], v[74:77]
	v_mfma_f32_16x16x32_bf16 v[70:73], v[172:175], v[212:215], v[70:73]
	v_mfma_f32_16x16x32_bf16 v[66:69], v[180:183], v[212:215], v[66:69]
	s_setprio 0
	s_barrier
	s_add_i32 s46, s37, s2
	v_lshl_add_u64 v[216:217], s[24:25], 0, v[134:135]
	s_mov_b32 m0, s46
	ds_read_b128 v[184:187], v151 offset:16384
	ds_read_b128 v[188:191], v151 offset:17408
	ds_read_b128 v[192:195], v151 offset:18432
	ds_read_b128 v[196:199], v151 offset:19456
	ds_read_b128 v[200:203], v151 offset:20480
	ds_read_b128 v[204:207], v151 offset:21504
	ds_read_b128 v[208:211], v151 offset:22528
	ds_read_b128 v[212:215], v151 offset:23552
	global_load_lds_dwordx4 v[216:217], off
	s_add_i32 m0, s46, 0x2000
	s_add_u32 s46, s24, 0x40000
	v_lshl_add_u64 v[218:219], s[24:25], 0, v[130:131]
	s_addc_u32 s47, s25, 0
	s_add_i32 s48, s38, s2
	global_load_lds_dwordx4 v[218:219], off
	v_lshl_add_u64 v[220:221], s[46:47], 0, v[134:135]
	s_mov_b32 m0, s48
	v_lshl_add_u64 v[222:223], s[26:27], 0, v[132:133]
	global_load_lds_dwordx4 v[220:221], off
	v_lshl_add_u64 v[220:221], s[46:47], 0, v[130:131]
	s_add_i32 m0, s48, 0x2000
	s_nop 0
	global_load_lds_dwordx4 v[220:221], off
	v_lshl_add_u64 v[220:221], s[26:27], 0, v[136:137]
	s_mov_b32 m0, s13
	s_nop 0
	global_load_lds_dwordx4 v[220:221], off
	s_mov_b32 m0, s28
	s_nop 0
	global_load_lds_dwordx4 v[222:223], off
	s_waitcnt vmcnt(8)
	s_waitcnt lgkmcnt(0)
	s_barrier
	s_setprio 1
	s_waitcnt lgkmcnt(0)
	v_mfma_f32_16x16x32_bf16 v[62:65], v[152:155], v[184:187], v[62:65]
	v_mfma_f32_16x16x32_bf16 v[58:61], v[160:163], v[184:187], v[58:61]
	v_mfma_f32_16x16x32_bf16 v[54:57], v[152:155], v[192:195], v[54:57]
	v_mfma_f32_16x16x32_bf16 v[50:53], v[160:163], v[192:195], v[50:53]
	v_mfma_f32_16x16x32_bf16 v[38:41], v[152:155], v[200:203], v[38:41]
	v_mfma_f32_16x16x32_bf16 v[34:37], v[160:163], v[200:203], v[34:37]
	v_mfma_f32_16x16x32_bf16 v[22:25], v[152:155], v[208:211], v[22:25]
	v_mfma_f32_16x16x32_bf16 v[18:21], v[160:163], v[208:211], v[18:21]
	v_mfma_f32_16x16x32_bf16 v[62:65], v[156:159], v[188:191], v[62:65]
	v_mfma_f32_16x16x32_bf16 v[58:61], v[164:167], v[188:191], v[58:61]
	v_mfma_f32_16x16x32_bf16 v[54:57], v[156:159], v[196:199], v[54:57]
	v_mfma_f32_16x16x32_bf16 v[50:53], v[164:167], v[196:199], v[50:53]
	v_mfma_f32_16x16x32_bf16 v[38:41], v[156:159], v[204:207], v[38:41]
	v_mfma_f32_16x16x32_bf16 v[34:37], v[164:167], v[204:207], v[34:37]
	v_mfma_f32_16x16x32_bf16 v[22:25], v[156:159], v[212:215], v[22:25]
	v_mfma_f32_16x16x32_bf16 v[18:21], v[164:167], v[212:215], v[18:21]
	s_setprio 0
	s_setprio 1
	v_mfma_f32_16x16x32_bf16 v[46:49], v[168:171], v[184:187], v[46:49]
	v_mfma_f32_16x16x32_bf16 v[42:45], v[176:179], v[184:187], v[42:45]
	v_mfma_f32_16x16x32_bf16 v[30:33], v[168:171], v[192:195], v[30:33]
	v_mfma_f32_16x16x32_bf16 v[26:29], v[176:179], v[192:195], v[26:29]
	v_mfma_f32_16x16x32_bf16 v[14:17], v[168:171], v[200:203], v[14:17]
	v_mfma_f32_16x16x32_bf16 v[10:13], v[176:179], v[200:203], v[10:13]
	v_mfma_f32_16x16x32_bf16 v[6:9], v[168:171], v[208:211], v[6:9]
	v_mfma_f32_16x16x32_bf16 v[2:5], v[176:179], v[208:211], v[2:5]
	v_mfma_f32_16x16x32_bf16 v[46:49], v[172:175], v[188:191], v[46:49]
	v_mfma_f32_16x16x32_bf16 v[42:45], v[180:183], v[188:191], v[42:45]
	v_mfma_f32_16x16x32_bf16 v[30:33], v[172:175], v[196:199], v[30:33]
	v_mfma_f32_16x16x32_bf16 v[26:29], v[180:183], v[196:199], v[26:29]
	v_mfma_f32_16x16x32_bf16 v[14:17], v[172:175], v[204:207], v[14:17]
	v_mfma_f32_16x16x32_bf16 v[10:13], v[180:183], v[204:207], v[10:13]
	v_mfma_f32_16x16x32_bf16 v[6:9], v[172:175], v[212:215], v[6:9]
	v_mfma_f32_16x16x32_bf16 v[2:5], v[180:183], v[212:215], v[2:5]
	s_setprio 0
	s_barrier
	s_add_i32 s46, 0, 0x18000
	s_add_i32 s47, 0, 0x1c000
	v_add_u32_e32 v164, s46, v147
	v_add_u32_e32 v180, s47, v147
	ds_read_b128 v[152:155], v164
	ds_read_b128 v[156:159], v164 offset:1024
	ds_read_b128 v[160:163], v164 offset:2048
	ds_read_b128 v[164:167], v164 offset:3072
	ds_read_b128 v[168:171], v180
	ds_read_b128 v[172:175], v180 offset:1024
	ds_read_b128 v[176:179], v180 offset:2048
	ds_read_b128 v[180:183], v180 offset:3072
	s_add_u32 s26, s26, 0x40000
	s_addc_u32 s27, s27, 0
	s_mov_b32 m0, s29
	v_lshl_add_u64 v[224:225], s[26:27], 0, v[136:137]
	ds_read_b128 v[184:187], v151 offset:32768
	ds_read_b128 v[188:191], v151 offset:33792
	ds_read_b128 v[192:195], v151 offset:34816
	ds_read_b128 v[196:199], v151 offset:35840
	ds_read_b128 v[200:203], v151 offset:36864
	ds_read_b128 v[204:207], v151 offset:37888
	ds_read_b128 v[208:211], v151 offset:38912
	ds_read_b128 v[212:215], v151 offset:39936
	global_load_lds_dwordx4 v[224:225], off
	v_lshl_add_u64 v[224:225], s[26:27], 0, v[132:133]
	s_mov_b32 m0, s30
	s_nop 0
	global_load_lds_dwordx4 v[224:225], off
	s_waitcnt vmcnt(8)
	s_waitcnt lgkmcnt(0)
	s_barrier
	s_setprio 1
	s_waitcnt lgkmcnt(0)
	v_mfma_f32_16x16x32_bf16 v[126:129], v[152:155], v[184:187], v[126:129]
	v_mfma_f32_16x16x32_bf16 v[122:125], v[160:163], v[184:187], v[122:125]
	v_mfma_f32_16x16x32_bf16 v[118:121], v[152:155], v[192:195], v[118:121]
	v_mfma_f32_16x16x32_bf16 v[114:117], v[160:163], v[192:195], v[114:117]
	v_mfma_f32_16x16x32_bf16 v[102:105], v[152:155], v[200:203], v[102:105]
	v_mfma_f32_16x16x32_bf16 v[98:101], v[160:163], v[200:203], v[98:101]
	v_mfma_f32_16x16x32_bf16 v[86:89], v[152:155], v[208:211], v[86:89]
	v_mfma_f32_16x16x32_bf16 v[82:85], v[160:163], v[208:211], v[82:85]
	v_mfma_f32_16x16x32_bf16 v[126:129], v[156:159], v[188:191], v[126:129]
	v_mfma_f32_16x16x32_bf16 v[122:125], v[164:167], v[188:191], v[122:125]
	v_mfma_f32_16x16x32_bf16 v[118:121], v[156:159], v[196:199], v[118:121]
	v_mfma_f32_16x16x32_bf16 v[114:117], v[164:167], v[196:199], v[114:117]
	v_mfma_f32_16x16x32_bf16 v[102:105], v[156:159], v[204:207], v[102:105]
	v_mfma_f32_16x16x32_bf16 v[98:101], v[164:167], v[204:207], v[98:101]
	v_mfma_f32_16x16x32_bf16 v[86:89], v[156:159], v[212:215], v[86:89]
	v_mfma_f32_16x16x32_bf16 v[82:85], v[164:167], v[212:215], v[82:85]
	s_setprio 0
	s_setprio 1
	v_mfma_f32_16x16x32_bf16 v[110:113], v[168:171], v[184:187], v[110:113]
	v_mfma_f32_16x16x32_bf16 v[106:109], v[176:179], v[184:187], v[106:109]
	v_mfma_f32_16x16x32_bf16 v[94:97], v[168:171], v[192:195], v[94:97]
	v_mfma_f32_16x16x32_bf16 v[90:93], v[176:179], v[192:195], v[90:93]
	v_mfma_f32_16x16x32_bf16 v[78:81], v[168:171], v[200:203], v[78:81]
	v_mfma_f32_16x16x32_bf16 v[74:77], v[176:179], v[200:203], v[74:77]
	v_mfma_f32_16x16x32_bf16 v[70:73], v[168:171], v[208:211], v[70:73]
	v_mfma_f32_16x16x32_bf16 v[66:69], v[176:179], v[208:211], v[66:69]
	v_mfma_f32_16x16x32_bf16 v[110:113], v[172:175], v[188:191], v[110:113]
	v_mfma_f32_16x16x32_bf16 v[106:109], v[180:183], v[188:191], v[106:109]
	v_mfma_f32_16x16x32_bf16 v[94:97], v[172:175], v[196:199], v[94:97]
	v_mfma_f32_16x16x32_bf16 v[90:93], v[180:183], v[196:199], v[90:93]
	v_mfma_f32_16x16x32_bf16 v[78:81], v[172:175], v[204:207], v[78:81]
	v_mfma_f32_16x16x32_bf16 v[74:77], v[180:183], v[204:207], v[74:77]
	v_mfma_f32_16x16x32_bf16 v[70:73], v[172:175], v[212:215], v[70:73]
	v_mfma_f32_16x16x32_bf16 v[66:69], v[180:183], v[212:215], v[66:69]
	s_setprio 0
	s_barrier
	s_add_i32 s26, s46, s2
	v_lshl_add_u64 v[216:217], v[216:217], 0, s[6:7]
	s_mov_b32 m0, s26
	ds_read_b128 v[184:187], v151 offset:49152
	ds_read_b128 v[188:191], v151 offset:50176
	ds_read_b128 v[192:195], v151 offset:51200
	ds_read_b128 v[196:199], v151 offset:52224
	ds_read_b128 v[200:203], v151 offset:53248
	ds_read_b128 v[204:207], v151 offset:54272
	ds_read_b128 v[208:211], v151 offset:55296
	ds_read_b128 v[212:215], v151 offset:56320
	global_load_lds_dwordx4 v[216:217], off
	s_add_i32 m0, s26, 0x2000
	s_add_u32 s24, s24, 0x40080
	v_lshl_add_u64 v[216:217], v[218:219], 0, s[6:7]
	s_addc_u32 s25, s25, 0
	s_add_i32 s26, s47, s2
	global_load_lds_dwordx4 v[216:217], off
	v_lshl_add_u64 v[216:217], s[24:25], 0, v[134:135]
	s_mov_b32 m0, s26
	s_nop 0
	global_load_lds_dwordx4 v[216:217], off
	v_lshl_add_u64 v[216:217], s[24:25], 0, v[130:131]
	s_add_i32 m0, s26, 0x2000
	s_nop 0
	global_load_lds_dwordx4 v[216:217], off
	v_lshl_add_u64 v[216:217], v[220:221], 0, s[6:7]
	s_mov_b32 m0, s34
	s_nop 0
	global_load_lds_dwordx4 v[216:217], off
	v_lshl_add_u64 v[216:217], v[222:223], 0, s[6:7]
	s_mov_b32 m0, s35
	s_nop 0
	global_load_lds_dwordx4 v[216:217], off
	s_waitcnt vmcnt(8)
	s_waitcnt lgkmcnt(0)
	s_barrier
	s_setprio 1
	s_waitcnt lgkmcnt(0)
	v_mfma_f32_16x16x32_bf16 v[62:65], v[152:155], v[184:187], v[62:65]
	v_mfma_f32_16x16x32_bf16 v[58:61], v[160:163], v[184:187], v[58:61]
	v_mfma_f32_16x16x32_bf16 v[54:57], v[152:155], v[192:195], v[54:57]
	v_mfma_f32_16x16x32_bf16 v[50:53], v[160:163], v[192:195], v[50:53]
	v_mfma_f32_16x16x32_bf16 v[38:41], v[152:155], v[200:203], v[38:41]
	v_mfma_f32_16x16x32_bf16 v[34:37], v[160:163], v[200:203], v[34:37]
	v_mfma_f32_16x16x32_bf16 v[22:25], v[152:155], v[208:211], v[22:25]
	v_mfma_f32_16x16x32_bf16 v[18:21], v[160:163], v[208:211], v[18:21]
	v_mfma_f32_16x16x32_bf16 v[62:65], v[156:159], v[188:191], v[62:65]
	v_mfma_f32_16x16x32_bf16 v[58:61], v[164:167], v[188:191], v[58:61]
	v_mfma_f32_16x16x32_bf16 v[54:57], v[156:159], v[196:199], v[54:57]
	v_mfma_f32_16x16x32_bf16 v[50:53], v[164:167], v[196:199], v[50:53]
	v_mfma_f32_16x16x32_bf16 v[38:41], v[156:159], v[204:207], v[38:41]
	v_mfma_f32_16x16x32_bf16 v[34:37], v[164:167], v[204:207], v[34:37]
	v_mfma_f32_16x16x32_bf16 v[22:25], v[156:159], v[212:215], v[22:25]
	v_mfma_f32_16x16x32_bf16 v[18:21], v[164:167], v[212:215], v[18:21]
	s_setprio 0
	s_setprio 1
	v_mfma_f32_16x16x32_bf16 v[46:49], v[168:171], v[184:187], v[46:49]
	v_mfma_f32_16x16x32_bf16 v[42:45], v[176:179], v[184:187], v[42:45]
	v_mfma_f32_16x16x32_bf16 v[30:33], v[168:171], v[192:195], v[30:33]
	v_mfma_f32_16x16x32_bf16 v[26:29], v[176:179], v[192:195], v[26:29]
	v_mfma_f32_16x16x32_bf16 v[14:17], v[168:171], v[200:203], v[14:17]
	v_mfma_f32_16x16x32_bf16 v[10:13], v[176:179], v[200:203], v[10:13]
	v_mfma_f32_16x16x32_bf16 v[6:9], v[168:171], v[208:211], v[6:9]
	v_mfma_f32_16x16x32_bf16 v[2:5], v[176:179], v[208:211], v[2:5]
	v_mfma_f32_16x16x32_bf16 v[46:49], v[172:175], v[188:191], v[46:49]
	v_mfma_f32_16x16x32_bf16 v[42:45], v[180:183], v[188:191], v[42:45]
	v_mfma_f32_16x16x32_bf16 v[30:33], v[172:175], v[196:199], v[30:33]
	v_mfma_f32_16x16x32_bf16 v[26:29], v[180:183], v[196:199], v[26:29]
	v_mfma_f32_16x16x32_bf16 v[14:17], v[172:175], v[204:207], v[14:17]
	v_mfma_f32_16x16x32_bf16 v[10:13], v[180:183], v[204:207], v[10:13]
	v_mfma_f32_16x16x32_bf16 v[6:9], v[172:175], v[212:215], v[6:9]
	v_mfma_f32_16x16x32_bf16 v[2:5], v[180:183], v[212:215], v[2:5]
	s_add_i32 s45, s45, 2
	s_add_u32 s22, s22, 0x100
	s_addc_u32 s23, s23, 0
	s_add_u32 s43, s43, 0x100
	s_addc_u32 s44, s44, 0
	s_cmp_gt_u32 s45, 13
	s_setprio 0
	s_barrier
	s_cbranch_scc0 .LBB0_395
	s_and_b64 vcc, exec, s[8:9]
	s_cbranch_vccz .LBB0_398
	s_barrier

.LBB0_419:
	ds_read_b128 v[144:147], v141
	ds_read_b128 v[148:151], v141 offset:1024
	ds_read_b128 v[152:155], v141 offset:2048
	ds_read_b128 v[156:159], v141 offset:3072
	ds_read_b128 v[160:163], v142
	ds_read_b128 v[164:167], v142 offset:1024
	ds_read_b128 v[168:171], v142 offset:2048
	ds_read_b128 v[172:175], v142 offset:3072
	s_add_u32 s24, s22, 0xfffc0080
	s_addc_u32 s25, s23, -1
	s_cmp_eq_u32 s43, 12
	s_cselect_b32 s27, s10, s25
	s_cselect_b32 s26, s11, s24
	s_cselect_b32 s25, s15, s42
	s_cselect_b32 s24, s17, s41
	v_lshl_add_u64 v[208:209], s[22:23], 0, v[134:135]
	s_add_i32 m0, s29, 0xc000
	ds_read_b128 v[176:179], v143
	ds_read_b128 v[180:183], v143 offset:1024
	ds_read_b128 v[184:187], v143 offset:2048
	ds_read_b128 v[188:191], v143 offset:3072
	ds_read_b128 v[192:195], v143 offset:4096
	ds_read_b128 v[196:199], v143 offset:5120
	ds_read_b128 v[200:203], v143 offset:6144
	ds_read_b128 v[204:207], v143 offset:7168
	global_load_lds_dwordx4 v[208:209], off
	v_lshl_add_u64 v[208:209], s[22:23], 0, v[136:137]
	s_add_i32 m0, s29, 0xe000
	s_nop 0
	global_load_lds_dwordx4 v[208:209], off
	s_waitcnt vmcnt(8)
	s_waitcnt lgkmcnt(0)
	s_barrier
	s_setprio 1
	s_waitcnt lgkmcnt(0)
	v_mfma_f32_16x16x32_bf16 v[126:129], v[144:147], v[176:179], v[126:129]
	v_mfma_f32_16x16x32_bf16 v[122:125], v[152:155], v[176:179], v[122:125]
	v_mfma_f32_16x16x32_bf16 v[118:121], v[144:147], v[184:187], v[118:121]
	v_mfma_f32_16x16x32_bf16 v[114:117], v[152:155], v[184:187], v[114:117]
	v_mfma_f32_16x16x32_bf16 v[106:109], v[144:147], v[192:195], v[106:109]
	v_mfma_f32_16x16x32_bf16 v[98:101], v[152:155], v[192:195], v[98:101]
	v_mfma_f32_16x16x32_bf16 v[90:93], v[144:147], v[200:203], v[90:93]
	v_mfma_f32_16x16x32_bf16 v[82:85], v[152:155], v[200:203], v[82:85]
	v_mfma_f32_16x16x32_bf16 v[126:129], v[148:151], v[180:183], v[126:129]
	v_mfma_f32_16x16x32_bf16 v[122:125], v[156:159], v[180:183], v[122:125]
	v_mfma_f32_16x16x32_bf16 v[118:121], v[148:151], v[188:191], v[118:121]
	v_mfma_f32_16x16x32_bf16 v[114:117], v[156:159], v[188:191], v[114:117]
	v_mfma_f32_16x16x32_bf16 v[106:109], v[148:151], v[196:199], v[106:109]
	v_mfma_f32_16x16x32_bf16 v[98:101], v[156:159], v[196:199], v[98:101]
	v_mfma_f32_16x16x32_bf16 v[90:93], v[148:151], v[204:207], v[90:93]
	v_mfma_f32_16x16x32_bf16 v[82:85], v[156:159], v[204:207], v[82:85]
	s_setprio 0
	s_setprio 1
	v_mfma_f32_16x16x32_bf16 v[110:113], v[160:163], v[176:179], v[110:113]
	v_mfma_f32_16x16x32_bf16 v[102:105], v[168:171], v[176:179], v[102:105]
	v_mfma_f32_16x16x32_bf16 v[94:97], v[160:163], v[184:187], v[94:97]
	v_mfma_f32_16x16x32_bf16 v[86:89], v[168:171], v[184:187], v[86:89]
	v_mfma_f32_16x16x32_bf16 v[78:81], v[160:163], v[192:195], v[78:81]
	v_mfma_f32_16x16x32_bf16 v[74:77], v[168:171], v[192:195], v[74:77]
	v_mfma_f32_16x16x32_bf16 v[70:73], v[160:163], v[200:203], v[70:73]
	v_mfma_f32_16x16x32_bf16 v[66:69], v[168:171], v[200:203], v[66:69]
	v_mfma_f32_16x16x32_bf16 v[110:113], v[164:167], v[180:183], v[110:113]
	v_mfma_f32_16x16x32_bf16 v[102:105], v[172:175], v[180:183], v[102:105]
	v_mfma_f32_16x16x32_bf16 v[94:97], v[164:167], v[188:191], v[94:97]
	v_mfma_f32_16x16x32_bf16 v[86:89], v[172:175], v[188:191], v[86:89]
	v_mfma_f32_16x16x32_bf16 v[78:81], v[164:167], v[196:199], v[78:81]
	v_mfma_f32_16x16x32_bf16 v[74:77], v[172:175], v[196:199], v[74:77]
	v_mfma_f32_16x16x32_bf16 v[70:73], v[164:167], v[204:207], v[70:73]
	v_mfma_f32_16x16x32_bf16 v[66:69], v[172:175], v[204:207], v[66:69]
	s_setprio 0
	s_barrier
	s_add_i32 s44, s39, s28
	v_lshl_add_u64 v[208:209], s[24:25], 0, v[130:131]
	s_mov_b32 m0, s44
	ds_read_b128 v[176:179], v143 offset:16384
	ds_read_b128 v[180:183], v143 offset:17408
	ds_read_b128 v[184:187], v143 offset:18432
	ds_read_b128 v[188:191], v143 offset:19456
	ds_read_b128 v[192:195], v143 offset:20480
	ds_read_b128 v[196:199], v143 offset:21504
	ds_read_b128 v[200:203], v143 offset:22528
	ds_read_b128 v[204:207], v143 offset:23552
	global_load_lds_dwordx4 v[208:209], off
	s_add_i32 m0, s44, 0x2000
	s_add_u32 s44, s24, 0x40000
	v_lshl_add_u64 v[210:211], s[24:25], 0, v[132:133]
	s_addc_u32 s45, s25, 0
	s_add_i32 s46, s40, s28
	global_load_lds_dwordx4 v[210:211], off
	v_lshl_add_u64 v[212:213], s[44:45], 0, v[130:131]
	s_mov_b32 m0, s46
	v_lshl_add_u64 v[214:215], s[26:27], 0, v[132:133]
	global_load_lds_dwordx4 v[212:213], off
	v_lshl_add_u64 v[212:213], s[44:45], 0, v[132:133]
	s_add_i32 m0, s46, 0x2000
	s_nop 0
	global_load_lds_dwordx4 v[212:213], off
	v_lshl_add_u64 v[212:213], s[26:27], 0, v[130:131]
	s_mov_b32 m0, s29
	s_nop 0
	global_load_lds_dwordx4 v[212:213], off
	s_mov_b32 m0, s30
	s_nop 0
	global_load_lds_dwordx4 v[214:215], off
	s_waitcnt vmcnt(8)
	s_waitcnt lgkmcnt(0)
	s_barrier
	s_setprio 1
	s_waitcnt lgkmcnt(0)
	v_mfma_f32_16x16x32_bf16 v[62:65], v[144:147], v[176:179], v[62:65]
	v_mfma_f32_16x16x32_bf16 v[58:61], v[152:155], v[176:179], v[58:61]
	v_mfma_f32_16x16x32_bf16 v[54:57], v[144:147], v[184:187], v[54:57]
	v_mfma_f32_16x16x32_bf16 v[50:53], v[152:155], v[184:187], v[50:53]
	v_mfma_f32_16x16x32_bf16 v[38:41], v[144:147], v[192:195], v[38:41]
	v_mfma_f32_16x16x32_bf16 v[34:37], v[152:155], v[192:195], v[34:37]
	v_mfma_f32_16x16x32_bf16 v[22:25], v[144:147], v[200:203], v[22:25]
	v_mfma_f32_16x16x32_bf16 v[18:21], v[152:155], v[200:203], v[18:21]
	v_mfma_f32_16x16x32_bf16 v[62:65], v[148:151], v[180:183], v[62:65]
	v_mfma_f32_16x16x32_bf16 v[58:61], v[156:159], v[180:183], v[58:61]
	v_mfma_f32_16x16x32_bf16 v[54:57], v[148:151], v[188:191], v[54:57]
	v_mfma_f32_16x16x32_bf16 v[50:53], v[156:159], v[188:191], v[50:53]
	v_mfma_f32_16x16x32_bf16 v[38:41], v[148:151], v[196:199], v[38:41]
	v_mfma_f32_16x16x32_bf16 v[34:37], v[156:159], v[196:199], v[34:37]
	v_mfma_f32_16x16x32_bf16 v[22:25], v[148:151], v[204:207], v[22:25]
	v_mfma_f32_16x16x32_bf16 v[18:21], v[156:159], v[204:207], v[18:21]
	s_setprio 0
	s_setprio 1
	v_mfma_f32_16x16x32_bf16 v[46:49], v[160:163], v[176:179], v[46:49]
	v_mfma_f32_16x16x32_bf16 v[42:45], v[168:171], v[176:179], v[42:45]
	v_mfma_f32_16x16x32_bf16 v[30:33], v[160:163], v[184:187], v[30:33]
	v_mfma_f32_16x16x32_bf16 v[26:29], v[168:171], v[184:187], v[26:29]
	v_mfma_f32_16x16x32_bf16 v[14:17], v[160:163], v[192:195], v[14:17]
	v_mfma_f32_16x16x32_bf16 v[10:13], v[168:171], v[192:195], v[10:13]
	v_mfma_f32_16x16x32_bf16 v[6:9], v[160:163], v[200:203], v[6:9]
	v_mfma_f32_16x16x32_bf16 v[2:5], v[168:171], v[200:203], v[2:5]
	v_mfma_f32_16x16x32_bf16 v[46:49], v[164:167], v[180:183], v[46:49]
	v_mfma_f32_16x16x32_bf16 v[42:45], v[172:175], v[180:183], v[42:45]
	v_mfma_f32_16x16x32_bf16 v[30:33], v[164:167], v[188:191], v[30:33]
	v_mfma_f32_16x16x32_bf16 v[26:29], v[172:175], v[188:191], v[26:29]
	v_mfma_f32_16x16x32_bf16 v[14:17], v[164:167], v[196:199], v[14:17]
	v_mfma_f32_16x16x32_bf16 v[10:13], v[172:175], v[196:199], v[10:13]
	v_mfma_f32_16x16x32_bf16 v[6:9], v[164:167], v[204:207], v[6:9]
	v_mfma_f32_16x16x32_bf16 v[2:5], v[172:175], v[204:207], v[2:5]
	s_setprio 0
	s_barrier
	s_add_i32 s44, 0, 0x18000
	s_add_i32 s45, 0, 0x1c000
	v_add_u32_e32 v156, s44, v139
	v_add_u32_e32 v172, s45, v139
	ds_read_b128 v[144:147], v156
	ds_read_b128 v[148:151], v156 offset:1024
	ds_read_b128 v[152:155], v156 offset:2048
	ds_read_b128 v[156:159], v156 offset:3072
	ds_read_b128 v[160:163], v172
	ds_read_b128 v[164:167], v172 offset:1024
	ds_read_b128 v[168:171], v172 offset:2048
	ds_read_b128 v[172:175], v172 offset:3072
	s_add_u32 s26, s26, 0x40000
	s_addc_u32 s27, s27, 0
	s_mov_b32 m0, s31
	v_lshl_add_u64 v[216:217], s[26:27], 0, v[130:131]
	ds_read_b128 v[176:179], v143 offset:32768
	ds_read_b128 v[180:183], v143 offset:33792
	ds_read_b128 v[184:187], v143 offset:34816
	ds_read_b128 v[188:191], v143 offset:35840
	ds_read_b128 v[192:195], v143 offset:36864
	ds_read_b128 v[196:199], v143 offset:37888
	ds_read_b128 v[200:203], v143 offset:38912
	ds_read_b128 v[204:207], v143 offset:39936
	global_load_lds_dwordx4 v[216:217], off
	v_lshl_add_u64 v[216:217], s[26:27], 0, v[132:133]
	s_mov_b32 m0, s34
	s_nop 0
	global_load_lds_dwordx4 v[216:217], off
	s_waitcnt vmcnt(8)
	s_waitcnt lgkmcnt(0)
	s_barrier
	s_setprio 1
	s_waitcnt lgkmcnt(0)
	v_mfma_f32_16x16x32_bf16 v[126:129], v[144:147], v[176:179], v[126:129]
	v_mfma_f32_16x16x32_bf16 v[122:125], v[152:155], v[176:179], v[122:125]
	v_mfma_f32_16x16x32_bf16 v[118:121], v[144:147], v[184:187], v[118:121]
	v_mfma_f32_16x16x32_bf16 v[114:117], v[152:155], v[184:187], v[114:117]
	v_mfma_f32_16x16x32_bf16 v[106:109], v[144:147], v[192:195], v[106:109]
	v_mfma_f32_16x16x32_bf16 v[98:101], v[152:155], v[192:195], v[98:101]
	v_mfma_f32_16x16x32_bf16 v[90:93], v[144:147], v[200:203], v[90:93]
	v_mfma_f32_16x16x32_bf16 v[82:85], v[152:155], v[200:203], v[82:85]
	v_mfma_f32_16x16x32_bf16 v[126:129], v[148:151], v[180:183], v[126:129]
	v_mfma_f32_16x16x32_bf16 v[122:125], v[156:159], v[180:183], v[122:125]
	v_mfma_f32_16x16x32_bf16 v[118:121], v[148:151], v[188:191], v[118:121]
	v_mfma_f32_16x16x32_bf16 v[114:117], v[156:159], v[188:191], v[114:117]
	v_mfma_f32_16x16x32_bf16 v[106:109], v[148:151], v[196:199], v[106:109]
	v_mfma_f32_16x16x32_bf16 v[98:101], v[156:159], v[196:199], v[98:101]
	v_mfma_f32_16x16x32_bf16 v[90:93], v[148:151], v[204:207], v[90:93]
	v_mfma_f32_16x16x32_bf16 v[82:85], v[156:159], v[204:207], v[82:85]
	s_setprio 0
	s_setprio 1
	v_mfma_f32_16x16x32_bf16 v[110:113], v[160:163], v[176:179], v[110:113]
	v_mfma_f32_16x16x32_bf16 v[102:105], v[168:171], v[176:179], v[102:105]
	v_mfma_f32_16x16x32_bf16 v[94:97], v[160:163], v[184:187], v[94:97]
	v_mfma_f32_16x16x32_bf16 v[86:89], v[168:171], v[184:187], v[86:89]
	v_mfma_f32_16x16x32_bf16 v[78:81], v[160:163], v[192:195], v[78:81]
	v_mfma_f32_16x16x32_bf16 v[74:77], v[168:171], v[192:195], v[74:77]
	v_mfma_f32_16x16x32_bf16 v[70:73], v[160:163], v[200:203], v[70:73]
	v_mfma_f32_16x16x32_bf16 v[66:69], v[168:171], v[200:203], v[66:69]
	v_mfma_f32_16x16x32_bf16 v[110:113], v[164:167], v[180:183], v[110:113]
	v_mfma_f32_16x16x32_bf16 v[102:105], v[172:175], v[180:183], v[102:105]
	v_mfma_f32_16x16x32_bf16 v[94:97], v[164:167], v[188:191], v[94:97]
	v_mfma_f32_16x16x32_bf16 v[86:89], v[172:175], v[188:191], v[86:89]
	v_mfma_f32_16x16x32_bf16 v[78:81], v[164:167], v[196:199], v[78:81]
	v_mfma_f32_16x16x32_bf16 v[74:77], v[172:175], v[196:199], v[74:77]
	v_mfma_f32_16x16x32_bf16 v[70:73], v[164:167], v[204:207], v[70:73]
	v_mfma_f32_16x16x32_bf16 v[66:69], v[172:175], v[204:207], v[66:69]
	s_setprio 0
	s_barrier
	s_add_i32 s26, s44, s28
	v_lshl_add_u64 v[208:209], v[208:209], 0, s[6:7]
	s_mov_b32 m0, s26
	ds_read_b128 v[176:179], v143 offset:49152
	ds_read_b128 v[180:183], v143 offset:50176
	ds_read_b128 v[184:187], v143 offset:51200
	ds_read_b128 v[188:191], v143 offset:52224
	ds_read_b128 v[192:195], v143 offset:53248
	ds_read_b128 v[196:199], v143 offset:54272
	ds_read_b128 v[200:203], v143 offset:55296
	ds_read_b128 v[204:207], v143 offset:56320
	global_load_lds_dwordx4 v[208:209], off
	s_add_i32 m0, s26, 0x2000
	s_add_u32 s24, s24, 0x40080
	v_lshl_add_u64 v[208:209], v[210:211], 0, s[6:7]
	s_addc_u32 s25, s25, 0
	s_add_i32 s26, s45, s28
	global_load_lds_dwordx4 v[208:209], off
	v_lshl_add_u64 v[208:209], s[24:25], 0, v[130:131]
	s_mov_b32 m0, s26
	s_nop 0
	global_load_lds_dwordx4 v[208:209], off
	v_lshl_add_u64 v[208:209], s[24:25], 0, v[132:133]
	s_add_i32 m0, s26, 0x2000
	s_nop 0
	global_load_lds_dwordx4 v[208:209], off
	v_lshl_add_u64 v[208:209], v[212:213], 0, s[6:7]
	s_mov_b32 m0, s36
	s_nop 0
	global_load_lds_dwordx4 v[208:209], off
	v_lshl_add_u64 v[208:209], v[214:215], 0, s[6:7]
	s_mov_b32 m0, s37
	s_nop 0
	global_load_lds_dwordx4 v[208:209], off
	s_waitcnt vmcnt(8)
	s_waitcnt lgkmcnt(0)
	s_barrier
	s_setprio 1
	s_waitcnt lgkmcnt(0)
	v_mfma_f32_16x16x32_bf16 v[62:65], v[144:147], v[176:179], v[62:65]
	v_mfma_f32_16x16x32_bf16 v[58:61], v[152:155], v[176:179], v[58:61]
	v_mfma_f32_16x16x32_bf16 v[54:57], v[144:147], v[184:187], v[54:57]
	v_mfma_f32_16x16x32_bf16 v[50:53], v[152:155], v[184:187], v[50:53]
	v_mfma_f32_16x16x32_bf16 v[38:41], v[144:147], v[192:195], v[38:41]
	v_mfma_f32_16x16x32_bf16 v[34:37], v[152:155], v[192:195], v[34:37]
	v_mfma_f32_16x16x32_bf16 v[22:25], v[144:147], v[200:203], v[22:25]
	v_mfma_f32_16x16x32_bf16 v[18:21], v[152:155], v[200:203], v[18:21]
	v_mfma_f32_16x16x32_bf16 v[62:65], v[148:151], v[180:183], v[62:65]
	v_mfma_f32_16x16x32_bf16 v[58:61], v[156:159], v[180:183], v[58:61]
	v_mfma_f32_16x16x32_bf16 v[54:57], v[148:151], v[188:191], v[54:57]
	v_mfma_f32_16x16x32_bf16 v[50:53], v[156:159], v[188:191], v[50:53]
	v_mfma_f32_16x16x32_bf16 v[38:41], v[148:151], v[196:199], v[38:41]
	v_mfma_f32_16x16x32_bf16 v[34:37], v[156:159], v[196:199], v[34:37]
	v_mfma_f32_16x16x32_bf16 v[22:25], v[148:151], v[204:207], v[22:25]
	v_mfma_f32_16x16x32_bf16 v[18:21], v[156:159], v[204:207], v[18:21]
	s_setprio 0
	s_setprio 1
	v_mfma_f32_16x16x32_bf16 v[46:49], v[160:163], v[176:179], v[46:49]
	v_mfma_f32_16x16x32_bf16 v[42:45], v[168:171], v[176:179], v[42:45]
	v_mfma_f32_16x16x32_bf16 v[30:33], v[160:163], v[184:187], v[30:33]
	v_mfma_f32_16x16x32_bf16 v[26:29], v[168:171], v[184:187], v[26:29]
	v_mfma_f32_16x16x32_bf16 v[14:17], v[160:163], v[192:195], v[14:17]
	v_mfma_f32_16x16x32_bf16 v[10:13], v[168:171], v[192:195], v[10:13]
	v_mfma_f32_16x16x32_bf16 v[6:9], v[160:163], v[200:203], v[6:9]
	v_mfma_f32_16x16x32_bf16 v[2:5], v[168:171], v[200:203], v[2:5]
	v_mfma_f32_16x16x32_bf16 v[46:49], v[164:167], v[180:183], v[46:49]
	v_mfma_f32_16x16x32_bf16 v[42:45], v[172:175], v[180:183], v[42:45]
	v_mfma_f32_16x16x32_bf16 v[30:33], v[164:167], v[188:191], v[30:33]
	v_mfma_f32_16x16x32_bf16 v[26:29], v[172:175], v[188:191], v[26:29]
	v_mfma_f32_16x16x32_bf16 v[14:17], v[164:167], v[196:199], v[14:17]
	v_mfma_f32_16x16x32_bf16 v[10:13], v[172:175], v[196:199], v[10:13]
	v_mfma_f32_16x16x32_bf16 v[6:9], v[164:167], v[204:207], v[6:9]
	v_mfma_f32_16x16x32_bf16 v[2:5], v[172:175], v[204:207], v[2:5]
	s_add_i32 s43, s43, 2
	s_add_u32 s22, s22, 0x100
	s_addc_u32 s23, s23, 0
	s_add_u32 s41, s41, 0x100
	s_addc_u32 s42, s42, 0
	s_cmp_gt_u32 s43, 13
	s_setprio 0
	s_barrier
	s_cbranch_scc0 .LBB0_419
	s_and_b64 vcc, exec, s[8:9]
	s_cbranch_vccz .LBB0_422
	s_barrier

.LBB0_567:
	ds_read_b128 v[152:155], v149
	ds_read_b128 v[156:159], v149 offset:1024
	ds_read_b128 v[160:163], v149 offset:2048
	ds_read_b128 v[164:167], v149 offset:3072
	ds_read_b128 v[168:171], v150
	ds_read_b128 v[172:175], v150 offset:1024
	ds_read_b128 v[176:179], v150 offset:2048
	ds_read_b128 v[180:183], v150 offset:3072
	s_add_u32 s18, s16, 0x100
	s_addc_u32 s19, s17, 0
	s_cmp_eq_u32 s42, 2
	s_cselect_b32 s23, s7, s19
	s_cselect_b32 s22, s6, s18
	s_cselect_b32 s21, s15, s41
	s_cselect_b32 s20, s14, s40
	v_lshl_add_u64 v[216:217], s[16:17], 0, v[138:139]
	s_add_i32 m0, s11, 0xc000
	ds_read_b128 v[184:187], v151
	ds_read_b128 v[188:191], v151 offset:1024
	ds_read_b128 v[192:195], v151 offset:2048
	ds_read_b128 v[196:199], v151 offset:3072
	ds_read_b128 v[200:203], v151 offset:4096
	ds_read_b128 v[204:207], v151 offset:5120
	ds_read_b128 v[208:211], v151 offset:6144
	ds_read_b128 v[212:215], v151 offset:7168
	global_load_lds_dwordx4 v[216:217], off
	v_lshl_add_u64 v[216:217], s[16:17], 0, v[140:141]
	s_add_i32 m0, s11, 0xe000
	s_nop 0
	global_load_lds_dwordx4 v[216:217], off
	s_waitcnt vmcnt(8)
	s_waitcnt lgkmcnt(0)
	s_barrier
	s_setprio 1
	s_waitcnt lgkmcnt(0)
	v_mfma_f32_16x16x32_bf16 v[126:129], v[152:155], v[184:187], v[126:129]
	v_mfma_f32_16x16x32_bf16 v[122:125], v[160:163], v[184:187], v[122:125]
	v_mfma_f32_16x16x32_bf16 v[118:121], v[152:155], v[192:195], v[118:121]
	v_mfma_f32_16x16x32_bf16 v[114:117], v[160:163], v[192:195], v[114:117]
	v_mfma_f32_16x16x32_bf16 v[102:105], v[152:155], v[200:203], v[102:105]
	v_mfma_f32_16x16x32_bf16 v[98:101], v[160:163], v[200:203], v[98:101]
	v_mfma_f32_16x16x32_bf16 v[86:89], v[152:155], v[208:211], v[86:89]
	v_mfma_f32_16x16x32_bf16 v[82:85], v[160:163], v[208:211], v[82:85]
	v_mfma_f32_16x16x32_bf16 v[126:129], v[156:159], v[188:191], v[126:129]
	v_mfma_f32_16x16x32_bf16 v[122:125], v[164:167], v[188:191], v[122:125]
	v_mfma_f32_16x16x32_bf16 v[118:121], v[156:159], v[196:199], v[118:121]
	v_mfma_f32_16x16x32_bf16 v[114:117], v[164:167], v[196:199], v[114:117]
	v_mfma_f32_16x16x32_bf16 v[102:105], v[156:159], v[204:207], v[102:105]
	v_mfma_f32_16x16x32_bf16 v[98:101], v[164:167], v[204:207], v[98:101]
	v_mfma_f32_16x16x32_bf16 v[86:89], v[156:159], v[212:215], v[86:89]
	v_mfma_f32_16x16x32_bf16 v[82:85], v[164:167], v[212:215], v[82:85]
	s_setprio 0
	s_setprio 1
	v_mfma_f32_16x16x32_bf16 v[110:113], v[168:171], v[184:187], v[110:113]
	v_mfma_f32_16x16x32_bf16 v[106:109], v[176:179], v[184:187], v[106:109]
	v_mfma_f32_16x16x32_bf16 v[94:97], v[168:171], v[192:195], v[94:97]
	v_mfma_f32_16x16x32_bf16 v[90:93], v[176:179], v[192:195], v[90:93]
	v_mfma_f32_16x16x32_bf16 v[78:81], v[168:171], v[200:203], v[78:81]
	v_mfma_f32_16x16x32_bf16 v[74:77], v[176:179], v[200:203], v[74:77]
	v_mfma_f32_16x16x32_bf16 v[70:73], v[168:171], v[208:211], v[70:73]
	v_mfma_f32_16x16x32_bf16 v[66:69], v[176:179], v[208:211], v[66:69]
	v_mfma_f32_16x16x32_bf16 v[110:113], v[172:175], v[188:191], v[110:113]
	v_mfma_f32_16x16x32_bf16 v[106:109], v[180:183], v[188:191], v[106:109]
	v_mfma_f32_16x16x32_bf16 v[94:97], v[172:175], v[196:199], v[94:97]
	v_mfma_f32_16x16x32_bf16 v[90:93], v[180:183], v[196:199], v[90:93]
	v_mfma_f32_16x16x32_bf16 v[78:81], v[172:175], v[204:207], v[78:81]
	v_mfma_f32_16x16x32_bf16 v[74:77], v[180:183], v[204:207], v[74:77]
	v_mfma_f32_16x16x32_bf16 v[70:73], v[172:175], v[212:215], v[70:73]
	v_mfma_f32_16x16x32_bf16 v[66:69], v[180:183], v[212:215], v[66:69]
	s_setprio 0
	s_barrier
	s_add_i32 s16, s34, s2
	v_lshl_add_u64 v[216:217], s[20:21], 0, v[134:135]
	s_mov_b32 m0, s16
	ds_read_b128 v[184:187], v151 offset:16384
	ds_read_b128 v[188:191], v151 offset:17408
	ds_read_b128 v[192:195], v151 offset:18432
	ds_read_b128 v[196:199], v151 offset:19456
	ds_read_b128 v[200:203], v151 offset:20480
	ds_read_b128 v[204:207], v151 offset:21504
	ds_read_b128 v[208:211], v151 offset:22528
	ds_read_b128 v[212:215], v151 offset:23552
	global_load_lds_dwordx4 v[216:217], off
	s_add_i32 m0, s16, 0x2000
	s_add_u32 s16, s20, 0x18000
	v_lshl_add_u64 v[218:219], s[20:21], 0, v[130:131]
	s_addc_u32 s17, s21, 0
	s_add_i32 s43, s35, s2
	global_load_lds_dwordx4 v[218:219], off
	v_lshl_add_u64 v[220:221], s[16:17], 0, v[134:135]
	s_mov_b32 m0, s43
	v_lshl_add_u64 v[222:223], s[22:23], 0, v[132:133]
	global_load_lds_dwordx4 v[220:221], off
	v_lshl_add_u64 v[220:221], s[16:17], 0, v[130:131]
	s_add_i32 m0, s43, 0x2000
	s_nop 0
	global_load_lds_dwordx4 v[220:221], off
	v_lshl_add_u64 v[220:221], s[22:23], 0, v[136:137]
	s_mov_b32 m0, s11
	s_nop 0
	global_load_lds_dwordx4 v[220:221], off
	s_mov_b32 m0, s24
	s_nop 0
	global_load_lds_dwordx4 v[222:223], off
	s_waitcnt vmcnt(8)
	s_waitcnt lgkmcnt(0)
	s_barrier
	s_setprio 1
	s_waitcnt lgkmcnt(0)
	v_mfma_f32_16x16x32_bf16 v[62:65], v[152:155], v[184:187], v[62:65]
	v_mfma_f32_16x16x32_bf16 v[58:61], v[160:163], v[184:187], v[58:61]
	v_mfma_f32_16x16x32_bf16 v[54:57], v[152:155], v[192:195], v[54:57]
	v_mfma_f32_16x16x32_bf16 v[50:53], v[160:163], v[192:195], v[50:53]
	v_mfma_f32_16x16x32_bf16 v[38:41], v[152:155], v[200:203], v[38:41]
	v_mfma_f32_16x16x32_bf16 v[34:37], v[160:163], v[200:203], v[34:37]
	v_mfma_f32_16x16x32_bf16 v[22:25], v[152:155], v[208:211], v[22:25]
	v_mfma_f32_16x16x32_bf16 v[18:21], v[160:163], v[208:211], v[18:21]
	v_mfma_f32_16x16x32_bf16 v[62:65], v[156:159], v[188:191], v[62:65]
	v_mfma_f32_16x16x32_bf16 v[58:61], v[164:167], v[188:191], v[58:61]
	v_mfma_f32_16x16x32_bf16 v[54:57], v[156:159], v[196:199], v[54:57]
	v_mfma_f32_16x16x32_bf16 v[50:53], v[164:167], v[196:199], v[50:53]
	v_mfma_f32_16x16x32_bf16 v[38:41], v[156:159], v[204:207], v[38:41]
	v_mfma_f32_16x16x32_bf16 v[34:37], v[164:167], v[204:207], v[34:37]
	v_mfma_f32_16x16x32_bf16 v[22:25], v[156:159], v[212:215], v[22:25]
	v_mfma_f32_16x16x32_bf16 v[18:21], v[164:167], v[212:215], v[18:21]
	s_setprio 0
	s_setprio 1
	v_mfma_f32_16x16x32_bf16 v[46:49], v[168:171], v[184:187], v[46:49]
	v_mfma_f32_16x16x32_bf16 v[42:45], v[176:179], v[184:187], v[42:45]
	v_mfma_f32_16x16x32_bf16 v[30:33], v[168:171], v[192:195], v[30:33]
	v_mfma_f32_16x16x32_bf16 v[26:29], v[176:179], v[192:195], v[26:29]
	v_mfma_f32_16x16x32_bf16 v[14:17], v[168:171], v[200:203], v[14:17]
	v_mfma_f32_16x16x32_bf16 v[10:13], v[176:179], v[200:203], v[10:13]
	v_mfma_f32_16x16x32_bf16 v[6:9], v[168:171], v[208:211], v[6:9]
	v_mfma_f32_16x16x32_bf16 v[2:5], v[176:179], v[208:211], v[2:5]
	v_mfma_f32_16x16x32_bf16 v[46:49], v[172:175], v[188:191], v[46:49]
	v_mfma_f32_16x16x32_bf16 v[42:45], v[180:183], v[188:191], v[42:45]
	v_mfma_f32_16x16x32_bf16 v[30:33], v[172:175], v[196:199], v[30:33]
	v_mfma_f32_16x16x32_bf16 v[26:29], v[180:183], v[196:199], v[26:29]
	v_mfma_f32_16x16x32_bf16 v[14:17], v[172:175], v[204:207], v[14:17]
	v_mfma_f32_16x16x32_bf16 v[10:13], v[180:183], v[204:207], v[10:13]
	v_mfma_f32_16x16x32_bf16 v[6:9], v[172:175], v[212:215], v[6:9]
	v_mfma_f32_16x16x32_bf16 v[2:5], v[180:183], v[212:215], v[2:5]
	s_setprio 0
	s_barrier
	s_add_i32 s43, 0, 0x18000
	s_add_i32 s44, 0, 0x1c000
	v_add_u32_e32 v164, s43, v147
	v_add_u32_e32 v180, s44, v147
	ds_read_b128 v[152:155], v164
	ds_read_b128 v[156:159], v164 offset:1024
	ds_read_b128 v[160:163], v164 offset:2048
	ds_read_b128 v[164:167], v164 offset:3072
	ds_read_b128 v[168:171], v180
	ds_read_b128 v[172:175], v180 offset:1024
	ds_read_b128 v[176:179], v180 offset:2048
	ds_read_b128 v[180:183], v180 offset:3072
	s_add_u32 s16, s22, 0x18000
	s_addc_u32 s17, s23, 0
	s_mov_b32 m0, s25
	v_lshl_add_u64 v[224:225], s[16:17], 0, v[136:137]
	ds_read_b128 v[184:187], v151 offset:32768
	ds_read_b128 v[188:191], v151 offset:33792
	ds_read_b128 v[192:195], v151 offset:34816
	ds_read_b128 v[196:199], v151 offset:35840
	ds_read_b128 v[200:203], v151 offset:36864
	ds_read_b128 v[204:207], v151 offset:37888
	ds_read_b128 v[208:211], v151 offset:38912
	ds_read_b128 v[212:215], v151 offset:39936
	global_load_lds_dwordx4 v[224:225], off
	v_lshl_add_u64 v[224:225], s[16:17], 0, v[132:133]
	s_mov_b32 m0, s26
	s_nop 0
	global_load_lds_dwordx4 v[224:225], off
	s_waitcnt vmcnt(8)
	s_waitcnt lgkmcnt(0)
	s_barrier
	s_setprio 1
	s_waitcnt lgkmcnt(0)
	v_mfma_f32_16x16x32_bf16 v[126:129], v[152:155], v[184:187], v[126:129]
	v_mfma_f32_16x16x32_bf16 v[122:125], v[160:163], v[184:187], v[122:125]
	v_mfma_f32_16x16x32_bf16 v[118:121], v[152:155], v[192:195], v[118:121]
	v_mfma_f32_16x16x32_bf16 v[114:117], v[160:163], v[192:195], v[114:117]
	v_mfma_f32_16x16x32_bf16 v[102:105], v[152:155], v[200:203], v[102:105]
	v_mfma_f32_16x16x32_bf16 v[98:101], v[160:163], v[200:203], v[98:101]
	v_mfma_f32_16x16x32_bf16 v[86:89], v[152:155], v[208:211], v[86:89]
	v_mfma_f32_16x16x32_bf16 v[82:85], v[160:163], v[208:211], v[82:85]
	v_mfma_f32_16x16x32_bf16 v[126:129], v[156:159], v[188:191], v[126:129]
	v_mfma_f32_16x16x32_bf16 v[122:125], v[164:167], v[188:191], v[122:125]
	v_mfma_f32_16x16x32_bf16 v[118:121], v[156:159], v[196:199], v[118:121]
	v_mfma_f32_16x16x32_bf16 v[114:117], v[164:167], v[196:199], v[114:117]
	v_mfma_f32_16x16x32_bf16 v[102:105], v[156:159], v[204:207], v[102:105]
	v_mfma_f32_16x16x32_bf16 v[98:101], v[164:167], v[204:207], v[98:101]
	v_mfma_f32_16x16x32_bf16 v[86:89], v[156:159], v[212:215], v[86:89]
	v_mfma_f32_16x16x32_bf16 v[82:85], v[164:167], v[212:215], v[82:85]
	s_setprio 0
	s_setprio 1
	v_mfma_f32_16x16x32_bf16 v[110:113], v[168:171], v[184:187], v[110:113]
	v_mfma_f32_16x16x32_bf16 v[106:109], v[176:179], v[184:187], v[106:109]
	v_mfma_f32_16x16x32_bf16 v[94:97], v[168:171], v[192:195], v[94:97]
	v_mfma_f32_16x16x32_bf16 v[90:93], v[176:179], v[192:195], v[90:93]
	v_mfma_f32_16x16x32_bf16 v[78:81], v[168:171], v[200:203], v[78:81]
	v_mfma_f32_16x16x32_bf16 v[74:77], v[176:179], v[200:203], v[74:77]
	v_mfma_f32_16x16x32_bf16 v[70:73], v[168:171], v[208:211], v[70:73]
	v_mfma_f32_16x16x32_bf16 v[66:69], v[176:179], v[208:211], v[66:69]
	v_mfma_f32_16x16x32_bf16 v[110:113], v[172:175], v[188:191], v[110:113]
	v_mfma_f32_16x16x32_bf16 v[106:109], v[180:183], v[188:191], v[106:109]
	v_mfma_f32_16x16x32_bf16 v[94:97], v[172:175], v[196:199], v[94:97]
	v_mfma_f32_16x16x32_bf16 v[90:93], v[180:183], v[196:199], v[90:93]
	v_mfma_f32_16x16x32_bf16 v[78:81], v[172:175], v[204:207], v[78:81]
	v_mfma_f32_16x16x32_bf16 v[74:77], v[180:183], v[204:207], v[74:77]
	v_mfma_f32_16x16x32_bf16 v[70:73], v[172:175], v[212:215], v[70:73]
	v_mfma_f32_16x16x32_bf16 v[66:69], v[180:183], v[212:215], v[66:69]
	s_setprio 0
	s_barrier
	s_add_i32 s16, s43, s2
	v_lshl_add_u64 v[216:217], v[216:217], 0, s[8:9]
	s_mov_b32 m0, s16
	ds_read_b128 v[184:187], v151 offset:49152
	ds_read_b128 v[188:191], v151 offset:50176
	ds_read_b128 v[192:195], v151 offset:51200
	ds_read_b128 v[196:199], v151 offset:52224
	ds_read_b128 v[200:203], v151 offset:53248
	ds_read_b128 v[204:207], v151 offset:54272
	ds_read_b128 v[208:211], v151 offset:55296
	ds_read_b128 v[212:215], v151 offset:56320
	global_load_lds_dwordx4 v[216:217], off
	s_add_i32 m0, s16, 0x2000
	s_add_u32 s16, s20, 0x18080
	v_lshl_add_u64 v[216:217], v[218:219], 0, s[8:9]
	s_addc_u32 s17, s21, 0
	s_add_i32 s20, s44, s2
	global_load_lds_dwordx4 v[216:217], off
	v_lshl_add_u64 v[216:217], s[16:17], 0, v[134:135]
	s_mov_b32 m0, s20
	s_nop 0
	global_load_lds_dwordx4 v[216:217], off
	v_lshl_add_u64 v[216:217], s[16:17], 0, v[130:131]
	s_add_i32 m0, s20, 0x2000
	s_nop 0
	global_load_lds_dwordx4 v[216:217], off
	v_lshl_add_u64 v[216:217], v[220:221], 0, s[8:9]
	s_mov_b32 m0, s28
	s_nop 0
	global_load_lds_dwordx4 v[216:217], off
	v_lshl_add_u64 v[216:217], v[222:223], 0, s[8:9]
	s_mov_b32 m0, s29
	s_nop 0
	global_load_lds_dwordx4 v[216:217], off
	s_waitcnt vmcnt(8)
	s_waitcnt lgkmcnt(0)
	s_barrier
	s_setprio 1
	s_waitcnt lgkmcnt(0)
	v_mfma_f32_16x16x32_bf16 v[62:65], v[152:155], v[184:187], v[62:65]
	v_mfma_f32_16x16x32_bf16 v[58:61], v[160:163], v[184:187], v[58:61]
	v_mfma_f32_16x16x32_bf16 v[54:57], v[152:155], v[192:195], v[54:57]
	v_mfma_f32_16x16x32_bf16 v[50:53], v[160:163], v[192:195], v[50:53]
	v_mfma_f32_16x16x32_bf16 v[38:41], v[152:155], v[200:203], v[38:41]
	v_mfma_f32_16x16x32_bf16 v[34:37], v[160:163], v[200:203], v[34:37]
	v_mfma_f32_16x16x32_bf16 v[22:25], v[152:155], v[208:211], v[22:25]
	v_mfma_f32_16x16x32_bf16 v[18:21], v[160:163], v[208:211], v[18:21]
	v_mfma_f32_16x16x32_bf16 v[62:65], v[156:159], v[188:191], v[62:65]
	v_mfma_f32_16x16x32_bf16 v[58:61], v[164:167], v[188:191], v[58:61]
	v_mfma_f32_16x16x32_bf16 v[54:57], v[156:159], v[196:199], v[54:57]
	v_mfma_f32_16x16x32_bf16 v[50:53], v[164:167], v[196:199], v[50:53]
	v_mfma_f32_16x16x32_bf16 v[38:41], v[156:159], v[204:207], v[38:41]
	v_mfma_f32_16x16x32_bf16 v[34:37], v[164:167], v[204:207], v[34:37]
	v_mfma_f32_16x16x32_bf16 v[22:25], v[156:159], v[212:215], v[22:25]
	v_mfma_f32_16x16x32_bf16 v[18:21], v[164:167], v[212:215], v[18:21]
	s_setprio 0
	s_setprio 1
	v_mfma_f32_16x16x32_bf16 v[46:49], v[168:171], v[184:187], v[46:49]
	v_mfma_f32_16x16x32_bf16 v[42:45], v[176:179], v[184:187], v[42:45]
	v_mfma_f32_16x16x32_bf16 v[30:33], v[168:171], v[192:195], v[30:33]
	v_mfma_f32_16x16x32_bf16 v[26:29], v[176:179], v[192:195], v[26:29]
	v_mfma_f32_16x16x32_bf16 v[14:17], v[168:171], v[200:203], v[14:17]
	v_mfma_f32_16x16x32_bf16 v[10:13], v[176:179], v[200:203], v[10:13]
	v_mfma_f32_16x16x32_bf16 v[6:9], v[168:171], v[208:211], v[6:9]
	v_mfma_f32_16x16x32_bf16 v[2:5], v[176:179], v[208:211], v[2:5]
	v_mfma_f32_16x16x32_bf16 v[46:49], v[172:175], v[188:191], v[46:49]
	v_mfma_f32_16x16x32_bf16 v[42:45], v[180:183], v[188:191], v[42:45]
	v_mfma_f32_16x16x32_bf16 v[30:33], v[172:175], v[196:199], v[30:33]
	v_mfma_f32_16x16x32_bf16 v[26:29], v[180:183], v[196:199], v[26:29]
	v_mfma_f32_16x16x32_bf16 v[14:17], v[172:175], v[204:207], v[14:17]
	v_mfma_f32_16x16x32_bf16 v[10:13], v[180:183], v[204:207], v[10:13]
	v_mfma_f32_16x16x32_bf16 v[6:9], v[172:175], v[212:215], v[6:9]
	v_mfma_f32_16x16x32_bf16 v[2:5], v[180:183], v[212:215], v[2:5]
	s_add_i32 s42, s42, 2
	s_add_u32 s40, s40, 0x100
	s_addc_u32 s41, s41, 0
	s_cmp_gt_u32 s42, 3
	s_mov_b64 s[16:17], s[18:19]
	s_setprio 0
	s_barrier
	s_cbranch_scc0 .LBB0_567
	s_and_b64 vcc, exec, s[12:13]
	s_cbranch_vccz .LBB0_570
	s_barrier

.LBB0_1033:
	ds_read_b128 v[146:149], v161
	ds_read_b128 v[150:153], v161 offset:1024
	ds_read_b128 v[154:157], v161 offset:2048
	ds_read_b128 v[164:167], v161 offset:3072
	ds_read_b128 v[168:171], v162
	ds_read_b128 v[172:175], v162 offset:1024
	ds_read_b128 v[176:179], v162 offset:2048
	ds_read_b128 v[180:183], v162 offset:3072
	s_add_u32 s28, s26, 0xfffc0080
	s_addc_u32 s29, s27, -1
	s_cmp_eq_u32 s43, 12
	s_cselect_b32 s31, s10, s29
	s_cselect_b32 s30, s11, s28
	s_cselect_b32 s29, s15, s42
	s_cselect_b32 s28, s17, s23
	v_lshl_add_u64 v[218:219], s[26:27], 0, v[138:139]
	s_add_i32 m0, s25, 0xc000
	ds_read_b128 v[184:187], v163
	ds_read_b128 v[188:191], v163 offset:1024
	ds_read_b128 v[192:195], v163 offset:2048
	ds_read_b128 v[196:199], v163 offset:3072
	ds_read_b128 v[202:205], v163 offset:4096
	ds_read_b128 v[206:209], v163 offset:5120
	ds_read_b128 v[210:213], v163 offset:6144
	ds_read_b128 v[214:217], v163 offset:7168
	global_load_lds_dwordx4 v[218:219], off
	v_lshl_add_u64 v[218:219], s[26:27], 0, v[140:141]
	s_add_i32 m0, s25, 0xe000
	s_nop 0
	global_load_lds_dwordx4 v[218:219], off
	s_waitcnt vmcnt(8)
	s_waitcnt lgkmcnt(0)
	s_barrier
	s_setprio 1
	s_waitcnt lgkmcnt(0)
	v_mfma_f32_16x16x32_bf16 v[126:129], v[146:149], v[184:187], v[126:129]
	v_mfma_f32_16x16x32_bf16 v[122:125], v[154:157], v[184:187], v[122:125]
	v_mfma_f32_16x16x32_bf16 v[118:121], v[146:149], v[192:195], v[118:121]
	v_mfma_f32_16x16x32_bf16 v[106:109], v[154:157], v[192:195], v[106:109]
	v_mfma_f32_16x16x32_bf16 v[102:105], v[146:149], v[202:205], v[102:105]
	v_mfma_f32_16x16x32_bf16 v[94:97], v[154:157], v[202:205], v[94:97]
	v_mfma_f32_16x16x32_bf16 v[86:89], v[146:149], v[210:213], v[86:89]
	v_mfma_f32_16x16x32_bf16 v[78:81], v[154:157], v[210:213], v[78:81]
	v_mfma_f32_16x16x32_bf16 v[126:129], v[150:153], v[188:191], v[126:129]
	v_mfma_f32_16x16x32_bf16 v[122:125], v[164:167], v[188:191], v[122:125]
	v_mfma_f32_16x16x32_bf16 v[118:121], v[150:153], v[196:199], v[118:121]
	v_mfma_f32_16x16x32_bf16 v[106:109], v[164:167], v[196:199], v[106:109]
	v_mfma_f32_16x16x32_bf16 v[102:105], v[150:153], v[206:209], v[102:105]
	v_mfma_f32_16x16x32_bf16 v[94:97], v[164:167], v[206:209], v[94:97]
	v_mfma_f32_16x16x32_bf16 v[86:89], v[150:153], v[214:217], v[86:89]
	v_mfma_f32_16x16x32_bf16 v[78:81], v[164:167], v[214:217], v[78:81]
	s_setprio 0
	s_setprio 1
	v_mfma_f32_16x16x32_bf16 v[114:117], v[168:171], v[184:187], v[114:117]
	v_mfma_f32_16x16x32_bf16 v[110:113], v[176:179], v[184:187], v[110:113]
	v_mfma_f32_16x16x32_bf16 v[98:101], v[168:171], v[192:195], v[98:101]
	v_mfma_f32_16x16x32_bf16 v[90:93], v[176:179], v[192:195], v[90:93]
	v_mfma_f32_16x16x32_bf16 v[82:85], v[168:171], v[202:205], v[82:85]
	v_mfma_f32_16x16x32_bf16 v[74:77], v[176:179], v[202:205], v[74:77]
	v_mfma_f32_16x16x32_bf16 v[70:73], v[168:171], v[210:213], v[70:73]
	v_mfma_f32_16x16x32_bf16 v[66:69], v[176:179], v[210:213], v[66:69]
	v_mfma_f32_16x16x32_bf16 v[114:117], v[172:175], v[188:191], v[114:117]
	v_mfma_f32_16x16x32_bf16 v[110:113], v[180:183], v[188:191], v[110:113]
	v_mfma_f32_16x16x32_bf16 v[98:101], v[172:175], v[196:199], v[98:101]
	v_mfma_f32_16x16x32_bf16 v[90:93], v[180:183], v[196:199], v[90:93]
	v_mfma_f32_16x16x32_bf16 v[82:85], v[172:175], v[206:209], v[82:85]
	v_mfma_f32_16x16x32_bf16 v[74:77], v[180:183], v[206:209], v[74:77]
	v_mfma_f32_16x16x32_bf16 v[70:73], v[172:175], v[214:217], v[70:73]
	v_mfma_f32_16x16x32_bf16 v[66:69], v[180:183], v[214:217], v[66:69]
	s_setprio 0
	s_barrier
	s_add_i32 s44, s80, s34
	v_lshl_add_u64 v[218:219], s[28:29], 0, v[132:133]
	s_mov_b32 m0, s44
	ds_read_b128 v[184:187], v163 offset:16384
	ds_read_b128 v[188:191], v163 offset:17408
	ds_read_b128 v[192:195], v163 offset:18432
	ds_read_b128 v[196:199], v163 offset:19456
	ds_read_b128 v[202:205], v163 offset:20480
	ds_read_b128 v[206:209], v163 offset:21504
	ds_read_b128 v[210:213], v163 offset:22528
	ds_read_b128 v[214:217], v163 offset:23552
	global_load_lds_dwordx4 v[218:219], off
	s_add_i32 m0, s44, 0x2000
	s_add_u32 s44, s28, 0x40000
	v_lshl_add_u64 v[220:221], s[28:29], 0, v[136:137]
	s_addc_u32 s45, s29, 0
	s_add_i32 s52, s51, s34
	global_load_lds_dwordx4 v[220:221], off
	v_lshl_add_u64 v[222:223], s[44:45], 0, v[132:133]
	s_mov_b32 m0, s52
	v_lshl_add_u64 v[224:225], s[30:31], 0, v[134:135]
	global_load_lds_dwordx4 v[222:223], off
	v_lshl_add_u64 v[222:223], s[44:45], 0, v[136:137]
	s_add_i32 m0, s52, 0x2000
	s_nop 0
	global_load_lds_dwordx4 v[222:223], off
	v_lshl_add_u64 v[222:223], s[30:31], 0, v[130:131]
	s_mov_b32 m0, s25
	s_nop 0
	global_load_lds_dwordx4 v[222:223], off
	s_mov_b32 m0, s35
	s_nop 0
	global_load_lds_dwordx4 v[224:225], off
	s_waitcnt vmcnt(8)
	s_waitcnt lgkmcnt(0)
	s_barrier
	s_setprio 1
	s_waitcnt lgkmcnt(0)
	v_mfma_f32_16x16x32_bf16 v[62:65], v[146:149], v[184:187], v[62:65]
	v_mfma_f32_16x16x32_bf16 v[58:61], v[154:157], v[184:187], v[58:61]
	v_mfma_f32_16x16x32_bf16 v[54:57], v[146:149], v[192:195], v[54:57]
	v_mfma_f32_16x16x32_bf16 v[50:53], v[154:157], v[192:195], v[50:53]
	v_mfma_f32_16x16x32_bf16 v[34:37], v[146:149], v[202:205], v[34:37]
	v_mfma_f32_16x16x32_bf16 v[30:33], v[154:157], v[202:205], v[30:33]
	v_mfma_f32_16x16x32_bf16 v[22:25], v[146:149], v[210:213], v[22:25]
	v_mfma_f32_16x16x32_bf16 v[14:17], v[154:157], v[210:213], v[14:17]
	v_mfma_f32_16x16x32_bf16 v[62:65], v[150:153], v[188:191], v[62:65]
	v_mfma_f32_16x16x32_bf16 v[58:61], v[164:167], v[188:191], v[58:61]
	v_mfma_f32_16x16x32_bf16 v[54:57], v[150:153], v[196:199], v[54:57]
	v_mfma_f32_16x16x32_bf16 v[50:53], v[164:167], v[196:199], v[50:53]
	v_mfma_f32_16x16x32_bf16 v[34:37], v[150:153], v[206:209], v[34:37]
	v_mfma_f32_16x16x32_bf16 v[30:33], v[164:167], v[206:209], v[30:33]
	v_mfma_f32_16x16x32_bf16 v[22:25], v[150:153], v[214:217], v[22:25]
	v_mfma_f32_16x16x32_bf16 v[14:17], v[164:167], v[214:217], v[14:17]
	s_setprio 0
	s_setprio 1
	v_mfma_f32_16x16x32_bf16 v[46:49], v[168:171], v[184:187], v[46:49]
	v_mfma_f32_16x16x32_bf16 v[42:45], v[176:179], v[184:187], v[42:45]
	v_mfma_f32_16x16x32_bf16 v[38:41], v[168:171], v[192:195], v[38:41]
	v_mfma_f32_16x16x32_bf16 v[26:29], v[176:179], v[192:195], v[26:29]
	v_mfma_f32_16x16x32_bf16 v[18:21], v[168:171], v[202:205], v[18:21]
	v_mfma_f32_16x16x32_bf16 v[10:13], v[176:179], v[202:205], v[10:13]
	v_mfma_f32_16x16x32_bf16 v[6:9], v[168:171], v[210:213], v[6:9]
	v_mfma_f32_16x16x32_bf16 v[2:5], v[176:179], v[210:213], v[2:5]
	v_mfma_f32_16x16x32_bf16 v[46:49], v[172:175], v[188:191], v[46:49]
	v_mfma_f32_16x16x32_bf16 v[42:45], v[180:183], v[188:191], v[42:45]
	v_mfma_f32_16x16x32_bf16 v[38:41], v[172:175], v[196:199], v[38:41]
	v_mfma_f32_16x16x32_bf16 v[26:29], v[180:183], v[196:199], v[26:29]
	v_mfma_f32_16x16x32_bf16 v[18:21], v[172:175], v[206:209], v[18:21]
	v_mfma_f32_16x16x32_bf16 v[10:13], v[180:183], v[206:209], v[10:13]
	v_mfma_f32_16x16x32_bf16 v[6:9], v[172:175], v[214:217], v[6:9]
	v_mfma_f32_16x16x32_bf16 v[2:5], v[180:183], v[214:217], v[2:5]
	s_setprio 0
	s_barrier
	s_add_i32 s44, 0, 0x18000
	s_add_i32 s45, 0, 0x1c000
	v_add_u32_e32 v164, s44, v159
	v_add_u32_e32 v180, s45, v159
	ds_read_b128 v[146:149], v164
	ds_read_b128 v[150:153], v164 offset:1024
	ds_read_b128 v[154:157], v164 offset:2048
	ds_read_b128 v[164:167], v164 offset:3072
	ds_read_b128 v[168:171], v180
	ds_read_b128 v[172:175], v180 offset:1024
	ds_read_b128 v[176:179], v180 offset:2048
	ds_read_b128 v[180:183], v180 offset:3072
	s_add_u32 s30, s30, 0x40000
	s_addc_u32 s31, s31, 0
	s_mov_b32 m0, s36
	v_lshl_add_u64 v[226:227], s[30:31], 0, v[130:131]
	ds_read_b128 v[184:187], v163 offset:32768
	ds_read_b128 v[188:191], v163 offset:33792
	ds_read_b128 v[192:195], v163 offset:34816
	ds_read_b128 v[196:199], v163 offset:35840
	ds_read_b128 v[202:205], v163 offset:36864
	ds_read_b128 v[206:209], v163 offset:37888
	ds_read_b128 v[210:213], v163 offset:38912
	ds_read_b128 v[214:217], v163 offset:39936
	global_load_lds_dwordx4 v[226:227], off
	v_lshl_add_u64 v[226:227], s[30:31], 0, v[134:135]
	s_mov_b32 m0, s37
	s_nop 0
	global_load_lds_dwordx4 v[226:227], off
	s_waitcnt vmcnt(8)
	s_waitcnt lgkmcnt(0)
	s_barrier
	s_setprio 1
	s_waitcnt lgkmcnt(0)
	v_mfma_f32_16x16x32_bf16 v[126:129], v[146:149], v[184:187], v[126:129]
	v_mfma_f32_16x16x32_bf16 v[122:125], v[154:157], v[184:187], v[122:125]
	v_mfma_f32_16x16x32_bf16 v[118:121], v[146:149], v[192:195], v[118:121]
	v_mfma_f32_16x16x32_bf16 v[106:109], v[154:157], v[192:195], v[106:109]
	v_mfma_f32_16x16x32_bf16 v[102:105], v[146:149], v[202:205], v[102:105]
	v_mfma_f32_16x16x32_bf16 v[94:97], v[154:157], v[202:205], v[94:97]
	v_mfma_f32_16x16x32_bf16 v[86:89], v[146:149], v[210:213], v[86:89]
	v_mfma_f32_16x16x32_bf16 v[78:81], v[154:157], v[210:213], v[78:81]
	v_mfma_f32_16x16x32_bf16 v[126:129], v[150:153], v[188:191], v[126:129]
	v_mfma_f32_16x16x32_bf16 v[122:125], v[164:167], v[188:191], v[122:125]
	v_mfma_f32_16x16x32_bf16 v[118:121], v[150:153], v[196:199], v[118:121]
	v_mfma_f32_16x16x32_bf16 v[106:109], v[164:167], v[196:199], v[106:109]
	v_mfma_f32_16x16x32_bf16 v[102:105], v[150:153], v[206:209], v[102:105]
	v_mfma_f32_16x16x32_bf16 v[94:97], v[164:167], v[206:209], v[94:97]
	v_mfma_f32_16x16x32_bf16 v[86:89], v[150:153], v[214:217], v[86:89]
	v_mfma_f32_16x16x32_bf16 v[78:81], v[164:167], v[214:217], v[78:81]
	s_setprio 0
	s_setprio 1
	v_mfma_f32_16x16x32_bf16 v[114:117], v[168:171], v[184:187], v[114:117]
	v_mfma_f32_16x16x32_bf16 v[110:113], v[176:179], v[184:187], v[110:113]
	v_mfma_f32_16x16x32_bf16 v[98:101], v[168:171], v[192:195], v[98:101]
	v_mfma_f32_16x16x32_bf16 v[90:93], v[176:179], v[192:195], v[90:93]
	v_mfma_f32_16x16x32_bf16 v[82:85], v[168:171], v[202:205], v[82:85]
	v_mfma_f32_16x16x32_bf16 v[74:77], v[176:179], v[202:205], v[74:77]
	v_mfma_f32_16x16x32_bf16 v[70:73], v[168:171], v[210:213], v[70:73]
	v_mfma_f32_16x16x32_bf16 v[66:69], v[176:179], v[210:213], v[66:69]
	v_mfma_f32_16x16x32_bf16 v[114:117], v[172:175], v[188:191], v[114:117]
	v_mfma_f32_16x16x32_bf16 v[110:113], v[180:183], v[188:191], v[110:113]
	v_mfma_f32_16x16x32_bf16 v[98:101], v[172:175], v[196:199], v[98:101]
	v_mfma_f32_16x16x32_bf16 v[90:93], v[180:183], v[196:199], v[90:93]
	v_mfma_f32_16x16x32_bf16 v[82:85], v[172:175], v[206:209], v[82:85]
	v_mfma_f32_16x16x32_bf16 v[74:77], v[180:183], v[206:209], v[74:77]
	v_mfma_f32_16x16x32_bf16 v[70:73], v[172:175], v[214:217], v[70:73]
	v_mfma_f32_16x16x32_bf16 v[66:69], v[180:183], v[214:217], v[66:69]
	s_setprio 0
	s_barrier
	s_add_i32 s30, s44, s34
	v_lshl_add_u64 v[218:219], v[218:219], 0, s[4:5]
	s_mov_b32 m0, s30
	ds_read_b128 v[184:187], v163 offset:49152
	ds_read_b128 v[188:191], v163 offset:50176
	ds_read_b128 v[192:195], v163 offset:51200
	ds_read_b128 v[196:199], v163 offset:52224
	ds_read_b128 v[202:205], v163 offset:53248
	ds_read_b128 v[206:209], v163 offset:54272
	ds_read_b128 v[210:213], v163 offset:55296
	ds_read_b128 v[214:217], v163 offset:56320
	global_load_lds_dwordx4 v[218:219], off
	s_add_i32 m0, s30, 0x2000
	s_add_u32 s28, s28, 0x40080
	v_lshl_add_u64 v[218:219], v[220:221], 0, s[4:5]
	s_addc_u32 s29, s29, 0
	s_add_i32 s30, s45, s34
	global_load_lds_dwordx4 v[218:219], off
	v_lshl_add_u64 v[218:219], s[28:29], 0, v[132:133]
	s_mov_b32 m0, s30
	s_nop 0
	global_load_lds_dwordx4 v[218:219], off
	v_lshl_add_u64 v[218:219], s[28:29], 0, v[136:137]
	s_add_i32 m0, s30, 0x2000
	s_nop 0
	global_load_lds_dwordx4 v[218:219], off
	v_lshl_add_u64 v[218:219], v[222:223], 0, s[4:5]
	s_mov_b32 m0, s39
	s_nop 0
	global_load_lds_dwordx4 v[218:219], off
	v_lshl_add_u64 v[218:219], v[224:225], 0, s[4:5]
	s_mov_b32 m0, s40
	s_nop 0
	global_load_lds_dwordx4 v[218:219], off
	s_waitcnt vmcnt(8)
	s_waitcnt lgkmcnt(0)
	s_barrier
	s_setprio 1
	s_waitcnt lgkmcnt(0)
	v_mfma_f32_16x16x32_bf16 v[62:65], v[146:149], v[184:187], v[62:65]
	v_mfma_f32_16x16x32_bf16 v[58:61], v[154:157], v[184:187], v[58:61]
	v_mfma_f32_16x16x32_bf16 v[54:57], v[146:149], v[192:195], v[54:57]
	v_mfma_f32_16x16x32_bf16 v[50:53], v[154:157], v[192:195], v[50:53]
	v_mfma_f32_16x16x32_bf16 v[34:37], v[146:149], v[202:205], v[34:37]
	v_mfma_f32_16x16x32_bf16 v[30:33], v[154:157], v[202:205], v[30:33]
	v_mfma_f32_16x16x32_bf16 v[22:25], v[146:149], v[210:213], v[22:25]
	v_mfma_f32_16x16x32_bf16 v[14:17], v[154:157], v[210:213], v[14:17]
	v_mfma_f32_16x16x32_bf16 v[62:65], v[150:153], v[188:191], v[62:65]
	v_mfma_f32_16x16x32_bf16 v[58:61], v[164:167], v[188:191], v[58:61]
	v_mfma_f32_16x16x32_bf16 v[54:57], v[150:153], v[196:199], v[54:57]
	v_mfma_f32_16x16x32_bf16 v[50:53], v[164:167], v[196:199], v[50:53]
	v_mfma_f32_16x16x32_bf16 v[34:37], v[150:153], v[206:209], v[34:37]
	v_mfma_f32_16x16x32_bf16 v[30:33], v[164:167], v[206:209], v[30:33]
	v_mfma_f32_16x16x32_bf16 v[22:25], v[150:153], v[214:217], v[22:25]
	v_mfma_f32_16x16x32_bf16 v[14:17], v[164:167], v[214:217], v[14:17]
	s_setprio 0
	s_setprio 1
	v_mfma_f32_16x16x32_bf16 v[46:49], v[168:171], v[184:187], v[46:49]
	v_mfma_f32_16x16x32_bf16 v[42:45], v[176:179], v[184:187], v[42:45]
	v_mfma_f32_16x16x32_bf16 v[38:41], v[168:171], v[192:195], v[38:41]
	v_mfma_f32_16x16x32_bf16 v[26:29], v[176:179], v[192:195], v[26:29]
	v_mfma_f32_16x16x32_bf16 v[18:21], v[168:171], v[202:205], v[18:21]
	v_mfma_f32_16x16x32_bf16 v[10:13], v[176:179], v[202:205], v[10:13]
	v_mfma_f32_16x16x32_bf16 v[6:9], v[168:171], v[210:213], v[6:9]
	v_mfma_f32_16x16x32_bf16 v[2:5], v[176:179], v[210:213], v[2:5]
	v_mfma_f32_16x16x32_bf16 v[46:49], v[172:175], v[188:191], v[46:49]
	v_mfma_f32_16x16x32_bf16 v[42:45], v[180:183], v[188:191], v[42:45]
	v_mfma_f32_16x16x32_bf16 v[38:41], v[172:175], v[196:199], v[38:41]
	v_mfma_f32_16x16x32_bf16 v[26:29], v[180:183], v[196:199], v[26:29]
	v_mfma_f32_16x16x32_bf16 v[18:21], v[172:175], v[206:209], v[18:21]
	v_mfma_f32_16x16x32_bf16 v[10:13], v[180:183], v[206:209], v[10:13]
	v_mfma_f32_16x16x32_bf16 v[6:9], v[172:175], v[214:217], v[6:9]
	v_mfma_f32_16x16x32_bf16 v[2:5], v[180:183], v[214:217], v[2:5]
	s_add_i32 s43, s43, 2
	s_add_u32 s26, s26, 0x100
	s_addc_u32 s27, s27, 0
	s_add_u32 s23, s23, 0x100
	s_addc_u32 s42, s42, 0
	s_cmp_gt_u32 s43, 13
	s_setprio 0
	s_barrier
	s_cbranch_scc0 .LBB0_1033
	v_readlane_b32 s60, v255, 1
	s_and_b64 vcc, exec, s[12:13]
	v_readlane_b32 s66, v255, 7
	v_readlane_b32 s67, v255, 8
	v_readlane_b32 s61, v255, 2
	v_readlane_b32 s62, v255, 3
	v_readlane_b32 s63, v255, 4
	v_readlane_b32 s64, v255, 5
	v_readlane_b32 s65, v255, 6
	v_readlane_b32 s68, v255, 9
	v_readlane_b32 s69, v255, 10
	v_readlane_b32 s70, v255, 11
	v_readlane_b32 s71, v255, 12
	v_readlane_b32 s72, v255, 13
	v_readlane_b32 s73, v255, 14
	v_readlane_b32 s74, v255, 15
	v_readlane_b32 s75, v255, 16
	s_cbranch_vccz .LBB0_1036
	s_barrier

.LBB0_1134:
	ds_read_b128 v[148:151], v169
	ds_read_b128 v[152:155], v169 offset:1024
	ds_read_b128 v[156:159], v169 offset:2048
	ds_read_b128 v[160:163], v169 offset:3072
	ds_read_b128 v[172:175], v170
	ds_read_b128 v[176:179], v170 offset:1024
	ds_read_b128 v[180:183], v170 offset:2048
	ds_read_b128 v[184:187], v170 offset:3072
	s_add_u32 s30, s12, 0xfffc0080
	s_addc_u32 s31, s13, -1
	s_cmp_eq_u32 s48, 12
	s_cselect_b32 s35, s3, s31
	s_cselect_b32 s34, s10, s30
	s_cselect_b32 s31, s11, s47
	s_cselect_b32 s30, s23, s25
	v_lshl_add_u64 v[222:223], s[12:13], 0, v[140:141]
	s_add_i32 m0, s36, 0xc000
	ds_read_b128 v[188:191], v171
	ds_read_b128 v[192:195], v171 offset:1024
	ds_read_b128 v[196:199], v171 offset:2048
	ds_read_b128 v[202:205], v171 offset:3072
	ds_read_b128 v[206:209], v171 offset:4096
	ds_read_b128 v[210:213], v171 offset:5120
	ds_read_b128 v[214:217], v171 offset:6144
	ds_read_b128 v[218:221], v171 offset:7168
	global_load_lds_dwordx4 v[222:223], off
	v_lshl_add_u64 v[222:223], s[12:13], 0, v[142:143]
	s_add_i32 m0, s36, 0xe000
	s_nop 0
	global_load_lds_dwordx4 v[222:223], off
	s_waitcnt vmcnt(8)
	s_waitcnt lgkmcnt(0)
	s_barrier
	s_setprio 1
	s_waitcnt lgkmcnt(0)
	v_mfma_f32_16x16x32_bf16 v[126:129], v[148:151], v[188:191], v[126:129]
	v_mfma_f32_16x16x32_bf16 v[122:125], v[156:159], v[188:191], v[122:125]
	v_mfma_f32_16x16x32_bf16 v[118:121], v[148:151], v[196:199], v[118:121]
	v_mfma_f32_16x16x32_bf16 v[110:113], v[156:159], v[196:199], v[110:113]
	v_mfma_f32_16x16x32_bf16 v[102:105], v[148:151], v[206:209], v[102:105]
	v_mfma_f32_16x16x32_bf16 v[94:97], v[156:159], v[206:209], v[94:97]
	v_mfma_f32_16x16x32_bf16 v[86:89], v[148:151], v[214:217], v[86:89]
	v_mfma_f32_16x16x32_bf16 v[78:81], v[156:159], v[214:217], v[78:81]
	v_mfma_f32_16x16x32_bf16 v[126:129], v[152:155], v[192:195], v[126:129]
	v_mfma_f32_16x16x32_bf16 v[122:125], v[160:163], v[192:195], v[122:125]
	v_mfma_f32_16x16x32_bf16 v[118:121], v[152:155], v[202:205], v[118:121]
	v_mfma_f32_16x16x32_bf16 v[110:113], v[160:163], v[202:205], v[110:113]
	v_mfma_f32_16x16x32_bf16 v[102:105], v[152:155], v[210:213], v[102:105]
	v_mfma_f32_16x16x32_bf16 v[94:97], v[160:163], v[210:213], v[94:97]
	v_mfma_f32_16x16x32_bf16 v[86:89], v[152:155], v[218:221], v[86:89]
	v_mfma_f32_16x16x32_bf16 v[78:81], v[160:163], v[218:221], v[78:81]
	s_setprio 0
	s_setprio 1
	v_mfma_f32_16x16x32_bf16 v[114:117], v[172:175], v[188:191], v[114:117]
	v_mfma_f32_16x16x32_bf16 v[106:109], v[180:183], v[188:191], v[106:109]
	v_mfma_f32_16x16x32_bf16 v[98:101], v[172:175], v[196:199], v[98:101]
	v_mfma_f32_16x16x32_bf16 v[90:93], v[180:183], v[196:199], v[90:93]
	v_mfma_f32_16x16x32_bf16 v[82:85], v[172:175], v[206:209], v[82:85]
	v_mfma_f32_16x16x32_bf16 v[74:77], v[180:183], v[206:209], v[74:77]
	v_mfma_f32_16x16x32_bf16 v[70:73], v[172:175], v[214:217], v[70:73]
	v_mfma_f32_16x16x32_bf16 v[66:69], v[180:183], v[214:217], v[66:69]
	v_mfma_f32_16x16x32_bf16 v[114:117], v[176:179], v[192:195], v[114:117]
	v_mfma_f32_16x16x32_bf16 v[106:109], v[184:187], v[192:195], v[106:109]
	v_mfma_f32_16x16x32_bf16 v[98:101], v[176:179], v[202:205], v[98:101]
	v_mfma_f32_16x16x32_bf16 v[90:93], v[184:187], v[202:205], v[90:93]
	v_mfma_f32_16x16x32_bf16 v[82:85], v[176:179], v[210:213], v[82:85]
	v_mfma_f32_16x16x32_bf16 v[74:77], v[184:187], v[210:213], v[74:77]
	v_mfma_f32_16x16x32_bf16 v[70:73], v[176:179], v[218:221], v[70:73]
	v_mfma_f32_16x16x32_bf16 v[66:69], v[184:187], v[218:221], v[66:69]
	s_setprio 0
	s_barrier
	s_add_i32 s49, s80, s21
	v_lshl_add_u64 v[222:223], s[30:31], 0, v[132:133]
	s_mov_b32 m0, s49
	ds_read_b128 v[188:191], v171 offset:16384
	ds_read_b128 v[192:195], v171 offset:17408
	ds_read_b128 v[196:199], v171 offset:18432
	ds_read_b128 v[202:205], v171 offset:19456
	ds_read_b128 v[206:209], v171 offset:20480
	ds_read_b128 v[210:213], v171 offset:21504
	ds_read_b128 v[214:217], v171 offset:22528
	ds_read_b128 v[218:221], v171 offset:23552
	global_load_lds_dwordx4 v[222:223], off
	s_add_i32 m0, s49, 0x2000
	s_add_u32 s50, s30, 0x40000
	v_lshl_add_u64 v[224:225], s[30:31], 0, v[136:137]
	s_addc_u32 s51, s31, 0
	s_add_i32 s49, s44, s21
	global_load_lds_dwordx4 v[224:225], off
	v_lshl_add_u64 v[226:227], s[50:51], 0, v[132:133]
	s_mov_b32 m0, s49
	v_lshl_add_u64 v[228:229], s[34:35], 0, v[134:135]
	global_load_lds_dwordx4 v[226:227], off
	v_lshl_add_u64 v[226:227], s[50:51], 0, v[136:137]
	s_add_i32 m0, s49, 0x2000
	s_nop 0
	global_load_lds_dwordx4 v[226:227], off
	v_lshl_add_u64 v[226:227], s[34:35], 0, v[130:131]
	s_mov_b32 m0, s36
	s_nop 0
	global_load_lds_dwordx4 v[226:227], off
	s_mov_b32 m0, s37
	s_nop 0
	global_load_lds_dwordx4 v[228:229], off
	s_waitcnt vmcnt(8)
	s_waitcnt lgkmcnt(0)
	s_barrier
	s_setprio 1
	s_waitcnt lgkmcnt(0)
	v_mfma_f32_16x16x32_bf16 v[62:65], v[148:151], v[188:191], v[62:65]
	v_mfma_f32_16x16x32_bf16 v[58:61], v[156:159], v[188:191], v[58:61]
	v_mfma_f32_16x16x32_bf16 v[54:57], v[148:151], v[196:199], v[54:57]
	v_mfma_f32_16x16x32_bf16 v[46:49], v[156:159], v[196:199], v[46:49]
	v_mfma_f32_16x16x32_bf16 v[38:41], v[148:151], v[206:209], v[38:41]
	v_mfma_f32_16x16x32_bf16 v[30:33], v[156:159], v[206:209], v[30:33]
	v_mfma_f32_16x16x32_bf16 v[22:25], v[148:151], v[214:217], v[22:25]
	v_mfma_f32_16x16x32_bf16 v[14:17], v[156:159], v[214:217], v[14:17]
	v_mfma_f32_16x16x32_bf16 v[62:65], v[152:155], v[192:195], v[62:65]
	v_mfma_f32_16x16x32_bf16 v[58:61], v[160:163], v[192:195], v[58:61]
	v_mfma_f32_16x16x32_bf16 v[54:57], v[152:155], v[202:205], v[54:57]
	v_mfma_f32_16x16x32_bf16 v[46:49], v[160:163], v[202:205], v[46:49]
	v_mfma_f32_16x16x32_bf16 v[38:41], v[152:155], v[210:213], v[38:41]
	v_mfma_f32_16x16x32_bf16 v[30:33], v[160:163], v[210:213], v[30:33]
	v_mfma_f32_16x16x32_bf16 v[22:25], v[152:155], v[218:221], v[22:25]
	v_mfma_f32_16x16x32_bf16 v[14:17], v[160:163], v[218:221], v[14:17]
	s_setprio 0
	s_setprio 1
	v_mfma_f32_16x16x32_bf16 v[50:53], v[172:175], v[188:191], v[50:53]
	v_mfma_f32_16x16x32_bf16 v[42:45], v[180:183], v[188:191], v[42:45]
	v_mfma_f32_16x16x32_bf16 v[34:37], v[172:175], v[196:199], v[34:37]
	v_mfma_f32_16x16x32_bf16 v[26:29], v[180:183], v[196:199], v[26:29]
	v_mfma_f32_16x16x32_bf16 v[18:21], v[172:175], v[206:209], v[18:21]
	v_mfma_f32_16x16x32_bf16 v[10:13], v[180:183], v[206:209], v[10:13]
	v_mfma_f32_16x16x32_bf16 v[6:9], v[172:175], v[214:217], v[6:9]
	v_mfma_f32_16x16x32_bf16 v[2:5], v[180:183], v[214:217], v[2:5]
	v_mfma_f32_16x16x32_bf16 v[50:53], v[176:179], v[192:195], v[50:53]
	v_mfma_f32_16x16x32_bf16 v[42:45], v[184:187], v[192:195], v[42:45]
	v_mfma_f32_16x16x32_bf16 v[34:37], v[176:179], v[202:205], v[34:37]
	v_mfma_f32_16x16x32_bf16 v[26:29], v[184:187], v[202:205], v[26:29]
	v_mfma_f32_16x16x32_bf16 v[18:21], v[176:179], v[210:213], v[18:21]
	v_mfma_f32_16x16x32_bf16 v[10:13], v[184:187], v[210:213], v[10:13]
	v_mfma_f32_16x16x32_bf16 v[6:9], v[176:179], v[218:221], v[6:9]
	v_mfma_f32_16x16x32_bf16 v[2:5], v[184:187], v[218:221], v[2:5]
	s_setprio 0
	s_barrier
	s_add_i32 s49, 0, 0x18000
	s_add_i32 s50, 0, 0x1c000
	v_add_u32_e32 v160, s49, v167
	v_add_u32_e32 v164, s50, v167
	ds_read_b128 v[148:151], v160
	ds_read_b128 v[152:155], v160 offset:1024
	ds_read_b128 v[156:159], v160 offset:2048
	ds_read_b128 v[160:163], v160 offset:3072
	ds_read_b128 v[172:175], v164
	ds_read_b128 v[176:179], v164 offset:1024
	ds_read_b128 v[180:183], v164 offset:2048
	ds_read_b128 v[184:187], v164 offset:3072
	s_add_u32 s34, s34, 0x40000
	s_addc_u32 s35, s35, 0
	s_mov_b32 m0, s38
	v_lshl_add_u64 v[230:231], s[34:35], 0, v[130:131]
	ds_read_b128 v[188:191], v171 offset:32768
	ds_read_b128 v[192:195], v171 offset:33792
	ds_read_b128 v[196:199], v171 offset:34816
	ds_read_b128 v[202:205], v171 offset:35840
	ds_read_b128 v[206:209], v171 offset:36864
	ds_read_b128 v[210:213], v171 offset:37888
	ds_read_b128 v[214:217], v171 offset:38912
	ds_read_b128 v[218:221], v171 offset:39936
	global_load_lds_dwordx4 v[230:231], off
	v_lshl_add_u64 v[230:231], s[34:35], 0, v[134:135]
	s_mov_b32 m0, s39
	s_nop 0
	global_load_lds_dwordx4 v[230:231], off
	s_waitcnt vmcnt(8)
	s_waitcnt lgkmcnt(0)
	s_barrier
	s_setprio 1
	s_waitcnt lgkmcnt(0)
	v_mfma_f32_16x16x32_bf16 v[126:129], v[148:151], v[188:191], v[126:129]
	v_mfma_f32_16x16x32_bf16 v[122:125], v[156:159], v[188:191], v[122:125]
	v_mfma_f32_16x16x32_bf16 v[118:121], v[148:151], v[196:199], v[118:121]
	v_mfma_f32_16x16x32_bf16 v[110:113], v[156:159], v[196:199], v[110:113]
	v_mfma_f32_16x16x32_bf16 v[102:105], v[148:151], v[206:209], v[102:105]
	v_mfma_f32_16x16x32_bf16 v[94:97], v[156:159], v[206:209], v[94:97]
	v_mfma_f32_16x16x32_bf16 v[86:89], v[148:151], v[214:217], v[86:89]
	v_mfma_f32_16x16x32_bf16 v[78:81], v[156:159], v[214:217], v[78:81]
	v_mfma_f32_16x16x32_bf16 v[126:129], v[152:155], v[192:195], v[126:129]
	v_mfma_f32_16x16x32_bf16 v[122:125], v[160:163], v[192:195], v[122:125]
	v_mfma_f32_16x16x32_bf16 v[118:121], v[152:155], v[202:205], v[118:121]
	v_mfma_f32_16x16x32_bf16 v[110:113], v[160:163], v[202:205], v[110:113]
	v_mfma_f32_16x16x32_bf16 v[102:105], v[152:155], v[210:213], v[102:105]
	v_mfma_f32_16x16x32_bf16 v[94:97], v[160:163], v[210:213], v[94:97]
	v_mfma_f32_16x16x32_bf16 v[86:89], v[152:155], v[218:221], v[86:89]
	v_mfma_f32_16x16x32_bf16 v[78:81], v[160:163], v[218:221], v[78:81]
	s_setprio 0
	s_setprio 1
	v_mfma_f32_16x16x32_bf16 v[114:117], v[172:175], v[188:191], v[114:117]
	v_mfma_f32_16x16x32_bf16 v[106:109], v[180:183], v[188:191], v[106:109]
	v_mfma_f32_16x16x32_bf16 v[98:101], v[172:175], v[196:199], v[98:101]
	v_mfma_f32_16x16x32_bf16 v[90:93], v[180:183], v[196:199], v[90:93]
	v_mfma_f32_16x16x32_bf16 v[82:85], v[172:175], v[206:209], v[82:85]
	v_mfma_f32_16x16x32_bf16 v[74:77], v[180:183], v[206:209], v[74:77]
	v_mfma_f32_16x16x32_bf16 v[70:73], v[172:175], v[214:217], v[70:73]
	v_mfma_f32_16x16x32_bf16 v[66:69], v[180:183], v[214:217], v[66:69]
	v_mfma_f32_16x16x32_bf16 v[114:117], v[176:179], v[192:195], v[114:117]
	v_mfma_f32_16x16x32_bf16 v[106:109], v[184:187], v[192:195], v[106:109]
	v_mfma_f32_16x16x32_bf16 v[98:101], v[176:179], v[202:205], v[98:101]
	v_mfma_f32_16x16x32_bf16 v[90:93], v[184:187], v[202:205], v[90:93]
	v_mfma_f32_16x16x32_bf16 v[82:85], v[176:179], v[210:213], v[82:85]
	v_mfma_f32_16x16x32_bf16 v[74:77], v[184:187], v[210:213], v[74:77]
	v_mfma_f32_16x16x32_bf16 v[70:73], v[176:179], v[218:221], v[70:73]
	v_mfma_f32_16x16x32_bf16 v[66:69], v[184:187], v[218:221], v[66:69]
	s_setprio 0
	s_barrier
	s_add_i32 s34, s49, s21
	v_lshl_add_u64 v[222:223], v[222:223], 0, s[14:15]
	s_mov_b32 m0, s34
	ds_read_b128 v[188:191], v171 offset:49152
	ds_read_b128 v[192:195], v171 offset:50176
	ds_read_b128 v[196:199], v171 offset:51200
	ds_read_b128 v[202:205], v171 offset:52224
	ds_read_b128 v[206:209], v171 offset:53248
	ds_read_b128 v[210:213], v171 offset:54272
	ds_read_b128 v[214:217], v171 offset:55296
	ds_read_b128 v[218:221], v171 offset:56320
	global_load_lds_dwordx4 v[222:223], off
	s_add_i32 m0, s34, 0x2000
	s_add_u32 s30, s30, 0x40080
	v_lshl_add_u64 v[222:223], v[224:225], 0, s[14:15]
	s_addc_u32 s31, s31, 0
	s_add_i32 s34, s50, s21
	global_load_lds_dwordx4 v[222:223], off
	v_lshl_add_u64 v[222:223], s[30:31], 0, v[132:133]
	s_mov_b32 m0, s34
	s_nop 0
	global_load_lds_dwordx4 v[222:223], off
	v_lshl_add_u64 v[222:223], s[30:31], 0, v[136:137]
	s_add_i32 m0, s34, 0x2000
	s_nop 0
	global_load_lds_dwordx4 v[222:223], off
	v_lshl_add_u64 v[222:223], v[226:227], 0, s[14:15]
	s_mov_b32 m0, s41
	s_nop 0
	global_load_lds_dwordx4 v[222:223], off
	v_lshl_add_u64 v[222:223], v[228:229], 0, s[14:15]
	s_mov_b32 m0, s42
	s_nop 0
	global_load_lds_dwordx4 v[222:223], off
	s_waitcnt vmcnt(8)
	s_waitcnt lgkmcnt(0)
	s_barrier
	s_setprio 1
	s_waitcnt lgkmcnt(0)
	v_mfma_f32_16x16x32_bf16 v[62:65], v[148:151], v[188:191], v[62:65]
	v_mfma_f32_16x16x32_bf16 v[58:61], v[156:159], v[188:191], v[58:61]
	v_mfma_f32_16x16x32_bf16 v[54:57], v[148:151], v[196:199], v[54:57]
	v_mfma_f32_16x16x32_bf16 v[46:49], v[156:159], v[196:199], v[46:49]
	v_mfma_f32_16x16x32_bf16 v[38:41], v[148:151], v[206:209], v[38:41]
	v_mfma_f32_16x16x32_bf16 v[30:33], v[156:159], v[206:209], v[30:33]
	v_mfma_f32_16x16x32_bf16 v[22:25], v[148:151], v[214:217], v[22:25]
	v_mfma_f32_16x16x32_bf16 v[14:17], v[156:159], v[214:217], v[14:17]
	v_mfma_f32_16x16x32_bf16 v[62:65], v[152:155], v[192:195], v[62:65]
	v_mfma_f32_16x16x32_bf16 v[58:61], v[160:163], v[192:195], v[58:61]
	v_mfma_f32_16x16x32_bf16 v[54:57], v[152:155], v[202:205], v[54:57]
	v_mfma_f32_16x16x32_bf16 v[46:49], v[160:163], v[202:205], v[46:49]
	v_mfma_f32_16x16x32_bf16 v[38:41], v[152:155], v[210:213], v[38:41]
	v_mfma_f32_16x16x32_bf16 v[30:33], v[160:163], v[210:213], v[30:33]
	v_mfma_f32_16x16x32_bf16 v[22:25], v[152:155], v[218:221], v[22:25]
	v_mfma_f32_16x16x32_bf16 v[14:17], v[160:163], v[218:221], v[14:17]
	s_setprio 0
	s_setprio 1
	v_mfma_f32_16x16x32_bf16 v[50:53], v[172:175], v[188:191], v[50:53]
	v_mfma_f32_16x16x32_bf16 v[42:45], v[180:183], v[188:191], v[42:45]
	v_mfma_f32_16x16x32_bf16 v[34:37], v[172:175], v[196:199], v[34:37]
	v_mfma_f32_16x16x32_bf16 v[26:29], v[180:183], v[196:199], v[26:29]
	v_mfma_f32_16x16x32_bf16 v[18:21], v[172:175], v[206:209], v[18:21]
	v_mfma_f32_16x16x32_bf16 v[10:13], v[180:183], v[206:209], v[10:13]
	v_mfma_f32_16x16x32_bf16 v[6:9], v[172:175], v[214:217], v[6:9]
	v_mfma_f32_16x16x32_bf16 v[2:5], v[180:183], v[214:217], v[2:5]
	v_mfma_f32_16x16x32_bf16 v[50:53], v[176:179], v[192:195], v[50:53]
	v_mfma_f32_16x16x32_bf16 v[42:45], v[184:187], v[192:195], v[42:45]
	v_mfma_f32_16x16x32_bf16 v[34:37], v[176:179], v[202:205], v[34:37]
	v_mfma_f32_16x16x32_bf16 v[26:29], v[184:187], v[202:205], v[26:29]
	v_mfma_f32_16x16x32_bf16 v[18:21], v[176:179], v[210:213], v[18:21]
	v_mfma_f32_16x16x32_bf16 v[10:13], v[184:187], v[210:213], v[10:13]
	v_mfma_f32_16x16x32_bf16 v[6:9], v[176:179], v[218:221], v[6:9]
	v_mfma_f32_16x16x32_bf16 v[2:5], v[184:187], v[218:221], v[2:5]
	s_add_i32 s48, s48, 2
	s_add_u32 s12, s12, 0x100
	s_addc_u32 s13, s13, 0
	s_add_u32 s25, s25, 0x100
	s_addc_u32 s47, s47, 0
	s_cmp_gt_u32 s48, 13
	s_setprio 0
	s_barrier
	s_cbranch_scc0 .LBB0_1134
	s_and_b64 vcc, exec, s[16:17]
	s_cbranch_vccz .LBB0_1137
	s_barrier

.LBB0_1299:
	ds_read_b128 v[106:109], v246
	ds_read_b128 v[118:121], v246 offset:1024
	ds_read_b128 v[122:125], v246 offset:2048
	ds_read_b128 v[134:137], v246 offset:3072
	ds_read_b128 v[138:141], v247
	ds_read_b128 v[142:145], v247 offset:1024
	ds_read_b128 v[146:149], v247 offset:2048
	ds_read_b128 v[158:161], v247 offset:3072
	s_add_u32 s30, s28, 0xfffe0080
	s_addc_u32 s31, s29, -1
	s_cmp_eq_u32 s49, 4
	s_cselect_b32 s35, s10, s31
	s_cselect_b32 s34, s11, s30
	s_cselect_b32 s31, s19, s48
	s_cselect_b32 s30, s21, s27
	v_lshl_add_u64 v[202:203], s[28:29], 0, v[198:199]
	s_add_i32 m0, s37, 0xc000
	ds_read_b128 v[162:165], v248
	ds_read_b128 v[166:169], v248 offset:1024
	ds_read_b128 v[170:173], v248 offset:2048
	ds_read_b128 v[174:177], v248 offset:3072
	ds_read_b128 v[178:181], v248 offset:4096
	ds_read_b128 v[182:185], v248 offset:5120
	ds_read_b128 v[186:189], v248 offset:6144
	ds_read_b128 v[206:209], v248 offset:7168
	global_load_lds_dwordx4 v[202:203], off
	v_lshl_add_u64 v[202:203], s[28:29], 0, v[200:201]
	s_add_i32 m0, s37, 0xe000
	s_nop 0
	global_load_lds_dwordx4 v[202:203], off
	s_waitcnt vmcnt(8)
	s_waitcnt lgkmcnt(0)
	s_barrier
	s_setprio 1
	s_waitcnt lgkmcnt(0)
	v_mfma_f32_16x16x32_bf16 v[154:157], v[106:109], v[162:165], v[154:157]
	v_mfma_f32_16x16x32_bf16 v[150:153], v[122:125], v[162:165], v[150:153]
	v_mfma_f32_16x16x32_bf16 v[114:117], v[106:109], v[170:173], v[114:117]
	v_mfma_f32_16x16x32_bf16 v[110:113], v[122:125], v[170:173], v[110:113]
	v_mfma_f32_16x16x32_bf16 v[94:97], v[106:109], v[178:181], v[94:97]
	v_mfma_f32_16x16x32_bf16 v[90:93], v[122:125], v[178:181], v[90:93]
	v_mfma_f32_16x16x32_bf16 v[78:81], v[106:109], v[186:189], v[78:81]
	v_mfma_f32_16x16x32_bf16 v[74:77], v[122:125], v[186:189], v[74:77]
	v_mfma_f32_16x16x32_bf16 v[154:157], v[118:121], v[166:169], v[154:157]
	v_mfma_f32_16x16x32_bf16 v[150:153], v[134:137], v[166:169], v[150:153]
	v_mfma_f32_16x16x32_bf16 v[114:117], v[118:121], v[174:177], v[114:117]
	v_mfma_f32_16x16x32_bf16 v[110:113], v[134:137], v[174:177], v[110:113]
	v_mfma_f32_16x16x32_bf16 v[94:97], v[118:121], v[182:185], v[94:97]
	v_mfma_f32_16x16x32_bf16 v[90:93], v[134:137], v[182:185], v[90:93]
	v_mfma_f32_16x16x32_bf16 v[78:81], v[118:121], v[206:209], v[78:81]
	v_mfma_f32_16x16x32_bf16 v[74:77], v[134:137], v[206:209], v[74:77]
	s_setprio 0
	s_setprio 1
	v_mfma_f32_16x16x32_bf16 v[130:133], v[138:141], v[162:165], v[130:133]
	v_mfma_f32_16x16x32_bf16 v[126:129], v[146:149], v[162:165], v[126:129]
	v_mfma_f32_16x16x32_bf16 v[102:105], v[138:141], v[170:173], v[102:105]
	v_mfma_f32_16x16x32_bf16 v[98:101], v[146:149], v[170:173], v[98:101]
	v_mfma_f32_16x16x32_bf16 v[86:89], v[138:141], v[178:181], v[86:89]
	v_mfma_f32_16x16x32_bf16 v[82:85], v[146:149], v[178:181], v[82:85]
	v_mfma_f32_16x16x32_bf16 v[70:73], v[138:141], v[186:189], v[70:73]
	v_mfma_f32_16x16x32_bf16 v[66:69], v[146:149], v[186:189], v[66:69]
	v_mfma_f32_16x16x32_bf16 v[130:133], v[142:145], v[166:169], v[130:133]
	v_mfma_f32_16x16x32_bf16 v[126:129], v[158:161], v[166:169], v[126:129]
	v_mfma_f32_16x16x32_bf16 v[102:105], v[142:145], v[174:177], v[102:105]
	v_mfma_f32_16x16x32_bf16 v[98:101], v[158:161], v[174:177], v[98:101]
	v_mfma_f32_16x16x32_bf16 v[86:89], v[142:145], v[182:185], v[86:89]
	v_mfma_f32_16x16x32_bf16 v[82:85], v[158:161], v[182:185], v[82:85]
	v_mfma_f32_16x16x32_bf16 v[70:73], v[142:145], v[206:209], v[70:73]
	v_mfma_f32_16x16x32_bf16 v[66:69], v[158:161], v[206:209], v[66:69]
	s_setprio 0
	s_barrier
	s_add_i32 s50, s80, s36
	v_lshl_add_u64 v[202:203], s[30:31], 0, v[192:193]
	s_mov_b32 m0, s50
	ds_read_b128 v[162:165], v248 offset:16384
	ds_read_b128 v[166:169], v248 offset:17408
	ds_read_b128 v[170:173], v248 offset:18432
	ds_read_b128 v[174:177], v248 offset:19456
	ds_read_b128 v[178:181], v248 offset:20480
	ds_read_b128 v[182:185], v248 offset:21504
	ds_read_b128 v[186:189], v248 offset:22528
	ds_read_b128 v[206:209], v248 offset:23552
	global_load_lds_dwordx4 v[202:203], off
	s_add_i32 m0, s50, 0x2000
	s_add_u32 s50, s30, 0x20000
	v_lshl_add_u64 v[204:205], s[30:31], 0, v[196:197]
	s_addc_u32 s51, s31, 0
	s_add_i32 s52, s46, s36
	global_load_lds_dwordx4 v[204:205], off
	v_lshl_add_u64 v[210:211], s[50:51], 0, v[192:193]
	s_mov_b32 m0, s52
	v_lshl_add_u64 v[212:213], s[34:35], 0, v[194:195]
	global_load_lds_dwordx4 v[210:211], off
	v_lshl_add_u64 v[210:211], s[50:51], 0, v[196:197]
	s_add_i32 m0, s52, 0x2000
	s_nop 0
	global_load_lds_dwordx4 v[210:211], off
	v_lshl_add_u64 v[210:211], s[34:35], 0, v[190:191]
	s_mov_b32 m0, s37
	s_nop 0
	global_load_lds_dwordx4 v[210:211], off
	s_mov_b32 m0, s38
	s_nop 0
	global_load_lds_dwordx4 v[212:213], off
	s_waitcnt vmcnt(8)
	s_waitcnt lgkmcnt(0)
	s_barrier
	s_setprio 1
	s_waitcnt lgkmcnt(0)
	v_mfma_f32_16x16x32_bf16 v[62:65], v[106:109], v[162:165], v[62:65]
	v_mfma_f32_16x16x32_bf16 v[58:61], v[122:125], v[162:165], v[58:61]
	v_mfma_f32_16x16x32_bf16 v[46:49], v[106:109], v[170:173], v[46:49]
	v_mfma_f32_16x16x32_bf16 v[42:45], v[122:125], v[170:173], v[42:45]
	v_mfma_f32_16x16x32_bf16 v[30:33], v[106:109], v[178:181], v[30:33]
	v_mfma_f32_16x16x32_bf16 v[26:29], v[122:125], v[178:181], v[26:29]
	v_mfma_f32_16x16x32_bf16 v[14:17], v[106:109], v[186:189], v[14:17]
	v_mfma_f32_16x16x32_bf16 v[10:13], v[122:125], v[186:189], v[10:13]
	v_mfma_f32_16x16x32_bf16 v[62:65], v[118:121], v[166:169], v[62:65]
	v_mfma_f32_16x16x32_bf16 v[58:61], v[134:137], v[166:169], v[58:61]
	v_mfma_f32_16x16x32_bf16 v[46:49], v[118:121], v[174:177], v[46:49]
	v_mfma_f32_16x16x32_bf16 v[42:45], v[134:137], v[174:177], v[42:45]
	v_mfma_f32_16x16x32_bf16 v[30:33], v[118:121], v[182:185], v[30:33]
	v_mfma_f32_16x16x32_bf16 v[26:29], v[134:137], v[182:185], v[26:29]
	v_mfma_f32_16x16x32_bf16 v[14:17], v[118:121], v[206:209], v[14:17]
	v_mfma_f32_16x16x32_bf16 v[10:13], v[134:137], v[206:209], v[10:13]
	s_setprio 0
	s_setprio 1
	v_mfma_f32_16x16x32_bf16 v[54:57], v[138:141], v[162:165], v[54:57]
	v_mfma_f32_16x16x32_bf16 v[50:53], v[146:149], v[162:165], v[50:53]
	v_mfma_f32_16x16x32_bf16 v[38:41], v[138:141], v[170:173], v[38:41]
	v_mfma_f32_16x16x32_bf16 v[34:37], v[146:149], v[170:173], v[34:37]
	v_mfma_f32_16x16x32_bf16 v[22:25], v[138:141], v[178:181], v[22:25]
	v_mfma_f32_16x16x32_bf16 v[18:21], v[146:149], v[178:181], v[18:21]
	v_mfma_f32_16x16x32_bf16 v[6:9], v[138:141], v[186:189], v[6:9]
	v_mfma_f32_16x16x32_bf16 v[2:5], v[146:149], v[186:189], v[2:5]
	v_mfma_f32_16x16x32_bf16 v[54:57], v[142:145], v[166:169], v[54:57]
	v_mfma_f32_16x16x32_bf16 v[50:53], v[158:161], v[166:169], v[50:53]
	v_mfma_f32_16x16x32_bf16 v[38:41], v[142:145], v[174:177], v[38:41]
	v_mfma_f32_16x16x32_bf16 v[34:37], v[158:161], v[174:177], v[34:37]
	v_mfma_f32_16x16x32_bf16 v[22:25], v[142:145], v[182:185], v[22:25]
	v_mfma_f32_16x16x32_bf16 v[18:21], v[158:161], v[182:185], v[18:21]
	v_mfma_f32_16x16x32_bf16 v[6:9], v[142:145], v[206:209], v[6:9]
	v_mfma_f32_16x16x32_bf16 v[2:5], v[158:161], v[206:209], v[2:5]
	s_setprio 0
	s_barrier
	s_add_i32 s50, 0, 0x18000
	s_add_i32 s51, 0, 0x1c000
	v_add_u32_e32 v134, s50, v244
	v_add_u32_e32 v158, s51, v244
	ds_read_b128 v[106:109], v134
	ds_read_b128 v[118:121], v134 offset:1024
	ds_read_b128 v[122:125], v134 offset:2048
	ds_read_b128 v[134:137], v134 offset:3072
	ds_read_b128 v[138:141], v158
	ds_read_b128 v[142:145], v158 offset:1024
	ds_read_b128 v[146:149], v158 offset:2048
	ds_read_b128 v[158:161], v158 offset:3072
	s_add_u32 s34, s34, 0x20000
	s_addc_u32 s35, s35, 0
	s_mov_b32 m0, s39
	v_lshl_add_u64 v[214:215], s[34:35], 0, v[190:191]
	ds_read_b128 v[162:165], v248 offset:32768
	ds_read_b128 v[166:169], v248 offset:33792
	ds_read_b128 v[170:173], v248 offset:34816
	ds_read_b128 v[174:177], v248 offset:35840
	ds_read_b128 v[178:181], v248 offset:36864
	ds_read_b128 v[182:185], v248 offset:37888
	ds_read_b128 v[186:189], v248 offset:38912
	ds_read_b128 v[206:209], v248 offset:39936
	global_load_lds_dwordx4 v[214:215], off
	v_lshl_add_u64 v[214:215], s[34:35], 0, v[194:195]
	s_mov_b32 m0, s40
	s_nop 0
	global_load_lds_dwordx4 v[214:215], off
	s_waitcnt vmcnt(8)
	s_waitcnt lgkmcnt(0)
	s_barrier
	s_setprio 1
	s_waitcnt lgkmcnt(0)
	v_mfma_f32_16x16x32_bf16 v[154:157], v[106:109], v[162:165], v[154:157]
	v_mfma_f32_16x16x32_bf16 v[150:153], v[122:125], v[162:165], v[150:153]
	v_mfma_f32_16x16x32_bf16 v[114:117], v[106:109], v[170:173], v[114:117]
	v_mfma_f32_16x16x32_bf16 v[110:113], v[122:125], v[170:173], v[110:113]
	v_mfma_f32_16x16x32_bf16 v[94:97], v[106:109], v[178:181], v[94:97]
	v_mfma_f32_16x16x32_bf16 v[90:93], v[122:125], v[178:181], v[90:93]
	v_mfma_f32_16x16x32_bf16 v[78:81], v[106:109], v[186:189], v[78:81]
	v_mfma_f32_16x16x32_bf16 v[74:77], v[122:125], v[186:189], v[74:77]
	v_mfma_f32_16x16x32_bf16 v[154:157], v[118:121], v[166:169], v[154:157]
	v_mfma_f32_16x16x32_bf16 v[150:153], v[134:137], v[166:169], v[150:153]
	v_mfma_f32_16x16x32_bf16 v[114:117], v[118:121], v[174:177], v[114:117]
	v_mfma_f32_16x16x32_bf16 v[110:113], v[134:137], v[174:177], v[110:113]
	v_mfma_f32_16x16x32_bf16 v[94:97], v[118:121], v[182:185], v[94:97]
	v_mfma_f32_16x16x32_bf16 v[90:93], v[134:137], v[182:185], v[90:93]
	v_mfma_f32_16x16x32_bf16 v[78:81], v[118:121], v[206:209], v[78:81]
	v_mfma_f32_16x16x32_bf16 v[74:77], v[134:137], v[206:209], v[74:77]
	s_setprio 0
	s_setprio 1
	v_mfma_f32_16x16x32_bf16 v[130:133], v[138:141], v[162:165], v[130:133]
	v_mfma_f32_16x16x32_bf16 v[126:129], v[146:149], v[162:165], v[126:129]
	v_mfma_f32_16x16x32_bf16 v[102:105], v[138:141], v[170:173], v[102:105]
	v_mfma_f32_16x16x32_bf16 v[98:101], v[146:149], v[170:173], v[98:101]
	v_mfma_f32_16x16x32_bf16 v[86:89], v[138:141], v[178:181], v[86:89]
	v_mfma_f32_16x16x32_bf16 v[82:85], v[146:149], v[178:181], v[82:85]
	v_mfma_f32_16x16x32_bf16 v[70:73], v[138:141], v[186:189], v[70:73]
	v_mfma_f32_16x16x32_bf16 v[66:69], v[146:149], v[186:189], v[66:69]
	v_mfma_f32_16x16x32_bf16 v[130:133], v[142:145], v[166:169], v[130:133]
	v_mfma_f32_16x16x32_bf16 v[126:129], v[158:161], v[166:169], v[126:129]
	v_mfma_f32_16x16x32_bf16 v[102:105], v[142:145], v[174:177], v[102:105]
	v_mfma_f32_16x16x32_bf16 v[98:101], v[158:161], v[174:177], v[98:101]
	v_mfma_f32_16x16x32_bf16 v[86:89], v[142:145], v[182:185], v[86:89]
	v_mfma_f32_16x16x32_bf16 v[82:85], v[158:161], v[182:185], v[82:85]
	v_mfma_f32_16x16x32_bf16 v[70:73], v[142:145], v[206:209], v[70:73]
	v_mfma_f32_16x16x32_bf16 v[66:69], v[158:161], v[206:209], v[66:69]
	s_setprio 0
	s_barrier
	s_add_i32 s34, s50, s36
	v_lshl_add_u64 v[202:203], v[202:203], 0, s[14:15]
	s_mov_b32 m0, s34
	ds_read_b128 v[162:165], v248 offset:49152
	ds_read_b128 v[166:169], v248 offset:50176
	ds_read_b128 v[170:173], v248 offset:51200
	ds_read_b128 v[174:177], v248 offset:52224
	ds_read_b128 v[178:181], v248 offset:53248
	ds_read_b128 v[182:185], v248 offset:54272
	ds_read_b128 v[186:189], v248 offset:55296
	ds_read_b128 v[206:209], v248 offset:56320
	global_load_lds_dwordx4 v[202:203], off
	s_add_i32 m0, s34, 0x2000
	s_add_u32 s30, s30, 0x20080
	v_lshl_add_u64 v[202:203], v[204:205], 0, s[14:15]
	s_addc_u32 s31, s31, 0
	s_add_i32 s34, s51, s36
	global_load_lds_dwordx4 v[202:203], off
	v_lshl_add_u64 v[202:203], s[30:31], 0, v[192:193]
	s_mov_b32 m0, s34
	s_nop 0
	global_load_lds_dwordx4 v[202:203], off
	v_lshl_add_u64 v[202:203], s[30:31], 0, v[196:197]
	s_add_i32 m0, s34, 0x2000
	s_nop 0
	global_load_lds_dwordx4 v[202:203], off
	v_lshl_add_u64 v[202:203], v[210:211], 0, s[14:15]
	s_mov_b32 m0, s42
	s_nop 0
	global_load_lds_dwordx4 v[202:203], off
	v_lshl_add_u64 v[202:203], v[212:213], 0, s[14:15]
	s_mov_b32 m0, s43
	s_nop 0
	global_load_lds_dwordx4 v[202:203], off
	s_waitcnt vmcnt(8)
	s_waitcnt lgkmcnt(0)
	s_barrier
	s_setprio 1
	s_waitcnt lgkmcnt(0)
	v_mfma_f32_16x16x32_bf16 v[62:65], v[106:109], v[162:165], v[62:65]
	v_mfma_f32_16x16x32_bf16 v[58:61], v[122:125], v[162:165], v[58:61]
	v_mfma_f32_16x16x32_bf16 v[46:49], v[106:109], v[170:173], v[46:49]
	v_mfma_f32_16x16x32_bf16 v[42:45], v[122:125], v[170:173], v[42:45]
	v_mfma_f32_16x16x32_bf16 v[30:33], v[106:109], v[178:181], v[30:33]
	v_mfma_f32_16x16x32_bf16 v[26:29], v[122:125], v[178:181], v[26:29]
	v_mfma_f32_16x16x32_bf16 v[14:17], v[106:109], v[186:189], v[14:17]
	v_mfma_f32_16x16x32_bf16 v[10:13], v[122:125], v[186:189], v[10:13]
	v_mfma_f32_16x16x32_bf16 v[62:65], v[118:121], v[166:169], v[62:65]
	v_mfma_f32_16x16x32_bf16 v[58:61], v[134:137], v[166:169], v[58:61]
	v_mfma_f32_16x16x32_bf16 v[46:49], v[118:121], v[174:177], v[46:49]
	v_mfma_f32_16x16x32_bf16 v[42:45], v[134:137], v[174:177], v[42:45]
	v_mfma_f32_16x16x32_bf16 v[30:33], v[118:121], v[182:185], v[30:33]
	v_mfma_f32_16x16x32_bf16 v[26:29], v[134:137], v[182:185], v[26:29]
	v_mfma_f32_16x16x32_bf16 v[14:17], v[118:121], v[206:209], v[14:17]
	v_mfma_f32_16x16x32_bf16 v[10:13], v[134:137], v[206:209], v[10:13]
	s_setprio 0
	s_setprio 1
	v_mfma_f32_16x16x32_bf16 v[54:57], v[138:141], v[162:165], v[54:57]
	v_mfma_f32_16x16x32_bf16 v[50:53], v[146:149], v[162:165], v[50:53]
	v_mfma_f32_16x16x32_bf16 v[38:41], v[138:141], v[170:173], v[38:41]
	v_mfma_f32_16x16x32_bf16 v[34:37], v[146:149], v[170:173], v[34:37]
	v_mfma_f32_16x16x32_bf16 v[22:25], v[138:141], v[178:181], v[22:25]
	v_mfma_f32_16x16x32_bf16 v[18:21], v[146:149], v[178:181], v[18:21]
	v_mfma_f32_16x16x32_bf16 v[6:9], v[138:141], v[186:189], v[6:9]
	v_mfma_f32_16x16x32_bf16 v[2:5], v[146:149], v[186:189], v[2:5]
	v_mfma_f32_16x16x32_bf16 v[54:57], v[142:145], v[166:169], v[54:57]
	v_mfma_f32_16x16x32_bf16 v[50:53], v[158:161], v[166:169], v[50:53]
	v_mfma_f32_16x16x32_bf16 v[38:41], v[142:145], v[174:177], v[38:41]
	v_mfma_f32_16x16x32_bf16 v[34:37], v[158:161], v[174:177], v[34:37]
	v_mfma_f32_16x16x32_bf16 v[22:25], v[142:145], v[182:185], v[22:25]
	v_mfma_f32_16x16x32_bf16 v[18:21], v[158:161], v[182:185], v[18:21]
	v_mfma_f32_16x16x32_bf16 v[6:9], v[142:145], v[206:209], v[6:9]
	v_mfma_f32_16x16x32_bf16 v[2:5], v[158:161], v[206:209], v[2:5]
	s_add_i32 s49, s49, 2
	s_add_u32 s28, s28, 0x100
	s_addc_u32 s29, s29, 0
	s_add_u32 s27, s27, 0x100
	s_addc_u32 s48, s48, 0
	s_cmp_gt_u32 s49, 5
	s_setprio 0
	s_barrier
	s_cbranch_scc0 .LBB0_1299
	s_and_b64 vcc, exec, s[16:17]
	s_cbranch_vccz .LBB0_1302
	s_barrier

.LBB0_1400:
	ds_read_b128 v[148:151], v169
	ds_read_b128 v[156:159], v169 offset:1024
	ds_read_b128 v[176:179], v169 offset:2048
	ds_read_b128 v[180:183], v169 offset:3072
	ds_read_b128 v[184:187], v173
	ds_read_b128 v[188:191], v173 offset:1024
	ds_read_b128 v[192:195], v173 offset:2048
	ds_read_b128 v[196:199], v173 offset:3072
	s_add_u32 s30, s4, 0xfffc0080
	s_addc_u32 s31, s5, -1
	s_cmp_eq_u32 s48, 12
	s_cselect_b32 s35, s3, s31
	s_cselect_b32 s34, s10, s30
	s_cselect_b32 s31, s11, s47
	s_cselect_b32 s30, s23, s25
	v_lshl_add_u64 v[152:153], s[4:5], 0, v[140:141]
	s_add_i32 m0, s36, 0xc000
	ds_read_b128 v[200:203], v175
	ds_read_b128 v[204:207], v175 offset:1024
	ds_read_b128 v[208:211], v175 offset:2048
	ds_read_b128 v[212:215], v175 offset:3072
	ds_read_b128 v[216:219], v175 offset:4096
	ds_read_b128 v[220:223], v175 offset:5120
	ds_read_b128 v[224:227], v175 offset:6144
	ds_read_b128 v[228:231], v175 offset:7168
	global_load_lds_dwordx4 v[152:153], off
	v_lshl_add_u64 v[152:153], s[4:5], 0, v[142:143]
	s_add_i32 m0, s36, 0xe000
	s_nop 0
	global_load_lds_dwordx4 v[152:153], off
	s_waitcnt vmcnt(8)
	s_waitcnt lgkmcnt(0)
	s_barrier
	s_setprio 1
	s_waitcnt lgkmcnt(0)
	v_mfma_f32_16x16x32_bf16 v[126:129], v[148:151], v[200:203], v[126:129]
	v_mfma_f32_16x16x32_bf16 v[122:125], v[176:179], v[200:203], v[122:125]
	v_mfma_f32_16x16x32_bf16 v[110:113], v[148:151], v[208:211], v[110:113]
	v_mfma_f32_16x16x32_bf16 v[106:109], v[176:179], v[208:211], v[106:109]
	v_mfma_f32_16x16x32_bf16 v[94:97], v[148:151], v[216:219], v[94:97]
	v_mfma_f32_16x16x32_bf16 v[90:93], v[176:179], v[216:219], v[90:93]
	v_mfma_f32_16x16x32_bf16 v[78:81], v[148:151], v[224:227], v[78:81]
	v_mfma_f32_16x16x32_bf16 v[74:77], v[176:179], v[224:227], v[74:77]
	v_mfma_f32_16x16x32_bf16 v[126:129], v[156:159], v[204:207], v[126:129]
	v_mfma_f32_16x16x32_bf16 v[122:125], v[180:183], v[204:207], v[122:125]
	v_mfma_f32_16x16x32_bf16 v[110:113], v[156:159], v[212:215], v[110:113]
	v_mfma_f32_16x16x32_bf16 v[106:109], v[180:183], v[212:215], v[106:109]
	v_mfma_f32_16x16x32_bf16 v[94:97], v[156:159], v[220:223], v[94:97]
	v_mfma_f32_16x16x32_bf16 v[90:93], v[180:183], v[220:223], v[90:93]
	v_mfma_f32_16x16x32_bf16 v[78:81], v[156:159], v[228:231], v[78:81]
	v_mfma_f32_16x16x32_bf16 v[74:77], v[180:183], v[228:231], v[74:77]
	s_setprio 0
	s_setprio 1
	v_mfma_f32_16x16x32_bf16 v[118:121], v[184:187], v[200:203], v[118:121]
	v_mfma_f32_16x16x32_bf16 v[114:117], v[192:195], v[200:203], v[114:117]
	v_mfma_f32_16x16x32_bf16 v[102:105], v[184:187], v[208:211], v[102:105]
	v_mfma_f32_16x16x32_bf16 v[98:101], v[192:195], v[208:211], v[98:101]
	v_mfma_f32_16x16x32_bf16 v[86:89], v[184:187], v[216:219], v[86:89]
	v_mfma_f32_16x16x32_bf16 v[82:85], v[192:195], v[216:219], v[82:85]
	v_mfma_f32_16x16x32_bf16 v[70:73], v[184:187], v[224:227], v[70:73]
	v_mfma_f32_16x16x32_bf16 v[66:69], v[192:195], v[224:227], v[66:69]
	v_mfma_f32_16x16x32_bf16 v[118:121], v[188:191], v[204:207], v[118:121]
	v_mfma_f32_16x16x32_bf16 v[114:117], v[196:199], v[204:207], v[114:117]
	v_mfma_f32_16x16x32_bf16 v[102:105], v[188:191], v[212:215], v[102:105]
	v_mfma_f32_16x16x32_bf16 v[98:101], v[196:199], v[212:215], v[98:101]
	v_mfma_f32_16x16x32_bf16 v[86:89], v[188:191], v[220:223], v[86:89]
	v_mfma_f32_16x16x32_bf16 v[82:85], v[196:199], v[220:223], v[82:85]
	v_mfma_f32_16x16x32_bf16 v[70:73], v[188:191], v[228:231], v[70:73]
	v_mfma_f32_16x16x32_bf16 v[66:69], v[196:199], v[228:231], v[66:69]
	s_setprio 0
	s_barrier
	s_add_i32 s49, s80, s21
	v_lshl_add_u64 v[152:153], s[30:31], 0, v[132:133]
	s_mov_b32 m0, s49
	ds_read_b128 v[200:203], v175 offset:16384
	ds_read_b128 v[204:207], v175 offset:17408
	ds_read_b128 v[208:211], v175 offset:18432
	ds_read_b128 v[212:215], v175 offset:19456
	ds_read_b128 v[216:219], v175 offset:20480
	ds_read_b128 v[220:223], v175 offset:21504
	ds_read_b128 v[224:227], v175 offset:22528
	ds_read_b128 v[228:231], v175 offset:23552
	global_load_lds_dwordx4 v[152:153], off
	s_add_i32 m0, s49, 0x2000
	s_add_u32 s50, s30, 0x40000
	v_lshl_add_u64 v[160:161], s[30:31], 0, v[136:137]
	s_addc_u32 s51, s31, 0
	s_add_i32 s49, s44, s21
	global_load_lds_dwordx4 v[160:161], off
	v_lshl_add_u64 v[164:165], s[50:51], 0, v[132:133]
	s_mov_b32 m0, s49
	v_lshl_add_u64 v[170:171], s[34:35], 0, v[134:135]
	global_load_lds_dwordx4 v[164:165], off
	v_lshl_add_u64 v[164:165], s[50:51], 0, v[136:137]
	s_add_i32 m0, s49, 0x2000
	s_nop 0
	global_load_lds_dwordx4 v[164:165], off
	v_lshl_add_u64 v[164:165], s[34:35], 0, v[130:131]
	s_mov_b32 m0, s36
	s_nop 0
	global_load_lds_dwordx4 v[164:165], off
	s_mov_b32 m0, s37
	s_nop 0
	global_load_lds_dwordx4 v[170:171], off
	s_waitcnt vmcnt(8)
	s_waitcnt lgkmcnt(0)
	s_barrier
	s_setprio 1
	s_waitcnt lgkmcnt(0)
	v_mfma_f32_16x16x32_bf16 v[62:65], v[148:151], v[200:203], v[62:65]
	v_mfma_f32_16x16x32_bf16 v[58:61], v[176:179], v[200:203], v[58:61]
	v_mfma_f32_16x16x32_bf16 v[46:49], v[148:151], v[208:211], v[46:49]
	v_mfma_f32_16x16x32_bf16 v[42:45], v[176:179], v[208:211], v[42:45]
	v_mfma_f32_16x16x32_bf16 v[30:33], v[148:151], v[216:219], v[30:33]
	v_mfma_f32_16x16x32_bf16 v[26:29], v[176:179], v[216:219], v[26:29]
	v_mfma_f32_16x16x32_bf16 v[14:17], v[148:151], v[224:227], v[14:17]
	v_mfma_f32_16x16x32_bf16 v[10:13], v[176:179], v[224:227], v[10:13]
	v_mfma_f32_16x16x32_bf16 v[62:65], v[156:159], v[204:207], v[62:65]
	v_mfma_f32_16x16x32_bf16 v[58:61], v[180:183], v[204:207], v[58:61]
	v_mfma_f32_16x16x32_bf16 v[46:49], v[156:159], v[212:215], v[46:49]
	v_mfma_f32_16x16x32_bf16 v[42:45], v[180:183], v[212:215], v[42:45]
	v_mfma_f32_16x16x32_bf16 v[30:33], v[156:159], v[220:223], v[30:33]
	v_mfma_f32_16x16x32_bf16 v[26:29], v[180:183], v[220:223], v[26:29]
	v_mfma_f32_16x16x32_bf16 v[14:17], v[156:159], v[228:231], v[14:17]
	v_mfma_f32_16x16x32_bf16 v[10:13], v[180:183], v[228:231], v[10:13]
	s_setprio 0
	s_setprio 1
	v_mfma_f32_16x16x32_bf16 v[54:57], v[184:187], v[200:203], v[54:57]
	v_mfma_f32_16x16x32_bf16 v[50:53], v[192:195], v[200:203], v[50:53]
	v_mfma_f32_16x16x32_bf16 v[38:41], v[184:187], v[208:211], v[38:41]
	v_mfma_f32_16x16x32_bf16 v[34:37], v[192:195], v[208:211], v[34:37]
	v_mfma_f32_16x16x32_bf16 v[22:25], v[184:187], v[216:219], v[22:25]
	v_mfma_f32_16x16x32_bf16 v[18:21], v[192:195], v[216:219], v[18:21]
	v_mfma_f32_16x16x32_bf16 v[6:9], v[184:187], v[224:227], v[6:9]
	v_mfma_f32_16x16x32_bf16 v[2:5], v[192:195], v[224:227], v[2:5]
	v_mfma_f32_16x16x32_bf16 v[54:57], v[188:191], v[204:207], v[54:57]
	v_mfma_f32_16x16x32_bf16 v[50:53], v[196:199], v[204:207], v[50:53]
	v_mfma_f32_16x16x32_bf16 v[38:41], v[188:191], v[212:215], v[38:41]
	v_mfma_f32_16x16x32_bf16 v[34:37], v[196:199], v[212:215], v[34:37]
	v_mfma_f32_16x16x32_bf16 v[22:25], v[188:191], v[220:223], v[22:25]
	v_mfma_f32_16x16x32_bf16 v[18:21], v[196:199], v[220:223], v[18:21]
	v_mfma_f32_16x16x32_bf16 v[6:9], v[188:191], v[228:231], v[6:9]
	v_mfma_f32_16x16x32_bf16 v[2:5], v[196:199], v[228:231], v[2:5]
	s_setprio 0
	s_barrier
	s_add_i32 s49, 0, 0x18000
	v_add_u32_e32 v154, s49, v163
	s_add_i32 s50, 0, 0x1c000
	ds_read_b128 v[148:151], v154
	ds_read_b128 v[156:159], v154 offset:1024
	ds_read_b128 v[176:179], v154 offset:2048
	ds_read_b128 v[180:183], v154 offset:3072
	v_add_u32_e32 v154, s50, v163
	ds_read_b128 v[184:187], v154
	ds_read_b128 v[188:191], v154 offset:1024
	ds_read_b128 v[192:195], v154 offset:2048
	ds_read_b128 v[196:199], v154 offset:3072
	s_add_u32 s34, s34, 0x40000
	s_addc_u32 s35, s35, 0
	s_mov_b32 m0, s38
	v_lshl_add_u64 v[232:233], s[34:35], 0, v[130:131]
	ds_read_b128 v[200:203], v175 offset:32768
	ds_read_b128 v[204:207], v175 offset:33792
	ds_read_b128 v[208:211], v175 offset:34816
	ds_read_b128 v[212:215], v175 offset:35840
	ds_read_b128 v[216:219], v175 offset:36864
	ds_read_b128 v[220:223], v175 offset:37888
	ds_read_b128 v[224:227], v175 offset:38912
	ds_read_b128 v[228:231], v175 offset:39936
	global_load_lds_dwordx4 v[232:233], off
	v_lshl_add_u64 v[232:233], s[34:35], 0, v[134:135]
	s_mov_b32 m0, s39
	s_nop 0
	global_load_lds_dwordx4 v[232:233], off
	s_waitcnt vmcnt(8)
	s_waitcnt lgkmcnt(0)
	s_barrier
	s_setprio 1
	s_waitcnt lgkmcnt(0)
	v_mfma_f32_16x16x32_bf16 v[126:129], v[148:151], v[200:203], v[126:129]
	v_mfma_f32_16x16x32_bf16 v[122:125], v[176:179], v[200:203], v[122:125]
	v_mfma_f32_16x16x32_bf16 v[110:113], v[148:151], v[208:211], v[110:113]
	v_mfma_f32_16x16x32_bf16 v[106:109], v[176:179], v[208:211], v[106:109]
	v_mfma_f32_16x16x32_bf16 v[94:97], v[148:151], v[216:219], v[94:97]
	v_mfma_f32_16x16x32_bf16 v[90:93], v[176:179], v[216:219], v[90:93]
	v_mfma_f32_16x16x32_bf16 v[78:81], v[148:151], v[224:227], v[78:81]
	v_mfma_f32_16x16x32_bf16 v[74:77], v[176:179], v[224:227], v[74:77]
	v_mfma_f32_16x16x32_bf16 v[126:129], v[156:159], v[204:207], v[126:129]
	v_mfma_f32_16x16x32_bf16 v[122:125], v[180:183], v[204:207], v[122:125]
	v_mfma_f32_16x16x32_bf16 v[110:113], v[156:159], v[212:215], v[110:113]
	v_mfma_f32_16x16x32_bf16 v[106:109], v[180:183], v[212:215], v[106:109]
	v_mfma_f32_16x16x32_bf16 v[94:97], v[156:159], v[220:223], v[94:97]
	v_mfma_f32_16x16x32_bf16 v[90:93], v[180:183], v[220:223], v[90:93]
	v_mfma_f32_16x16x32_bf16 v[78:81], v[156:159], v[228:231], v[78:81]
	v_mfma_f32_16x16x32_bf16 v[74:77], v[180:183], v[228:231], v[74:77]
	s_setprio 0
	s_setprio 1
	v_mfma_f32_16x16x32_bf16 v[118:121], v[184:187], v[200:203], v[118:121]
	v_mfma_f32_16x16x32_bf16 v[114:117], v[192:195], v[200:203], v[114:117]
	v_mfma_f32_16x16x32_bf16 v[102:105], v[184:187], v[208:211], v[102:105]
	v_mfma_f32_16x16x32_bf16 v[98:101], v[192:195], v[208:211], v[98:101]
	v_mfma_f32_16x16x32_bf16 v[86:89], v[184:187], v[216:219], v[86:89]
	v_mfma_f32_16x16x32_bf16 v[82:85], v[192:195], v[216:219], v[82:85]
	v_mfma_f32_16x16x32_bf16 v[70:73], v[184:187], v[224:227], v[70:73]
	v_mfma_f32_16x16x32_bf16 v[66:69], v[192:195], v[224:227], v[66:69]
	v_mfma_f32_16x16x32_bf16 v[118:121], v[188:191], v[204:207], v[118:121]
	v_mfma_f32_16x16x32_bf16 v[114:117], v[196:199], v[204:207], v[114:117]
	v_mfma_f32_16x16x32_bf16 v[102:105], v[188:191], v[212:215], v[102:105]
	v_mfma_f32_16x16x32_bf16 v[98:101], v[196:199], v[212:215], v[98:101]
	v_mfma_f32_16x16x32_bf16 v[86:89], v[188:191], v[220:223], v[86:89]
	v_mfma_f32_16x16x32_bf16 v[82:85], v[196:199], v[220:223], v[82:85]
	v_mfma_f32_16x16x32_bf16 v[70:73], v[188:191], v[228:231], v[70:73]
	v_mfma_f32_16x16x32_bf16 v[66:69], v[196:199], v[228:231], v[66:69]
	s_setprio 0
	s_barrier
	s_add_i32 s34, s49, s21
	v_lshl_add_u64 v[152:153], v[152:153], 0, s[14:15]
	s_mov_b32 m0, s34
	ds_read_b128 v[200:203], v175 offset:49152
	ds_read_b128 v[204:207], v175 offset:50176
	ds_read_b128 v[208:211], v175 offset:51200
	ds_read_b128 v[212:215], v175 offset:52224
	ds_read_b128 v[216:219], v175 offset:53248
	ds_read_b128 v[220:223], v175 offset:54272
	ds_read_b128 v[224:227], v175 offset:55296
	ds_read_b128 v[228:231], v175 offset:56320
	global_load_lds_dwordx4 v[152:153], off
	s_add_i32 m0, s34, 0x2000
	s_add_u32 s30, s30, 0x40080
	v_lshl_add_u64 v[152:153], v[160:161], 0, s[14:15]
	s_addc_u32 s31, s31, 0
	s_add_i32 s34, s50, s21
	global_load_lds_dwordx4 v[152:153], off
	v_lshl_add_u64 v[152:153], s[30:31], 0, v[132:133]
	s_mov_b32 m0, s34
	s_nop 0
	global_load_lds_dwordx4 v[152:153], off
	v_lshl_add_u64 v[152:153], s[30:31], 0, v[136:137]
	s_add_i32 m0, s34, 0x2000
	s_nop 0
	global_load_lds_dwordx4 v[152:153], off
	v_lshl_add_u64 v[152:153], v[164:165], 0, s[14:15]
	s_mov_b32 m0, s41
	s_nop 0
	global_load_lds_dwordx4 v[152:153], off
	v_lshl_add_u64 v[152:153], v[170:171], 0, s[14:15]
	s_mov_b32 m0, s42
	s_nop 0
	global_load_lds_dwordx4 v[152:153], off
	s_waitcnt vmcnt(8)
	s_waitcnt lgkmcnt(0)
	s_barrier
	s_setprio 1
	s_waitcnt lgkmcnt(0)
	v_mfma_f32_16x16x32_bf16 v[62:65], v[148:151], v[200:203], v[62:65]
	v_mfma_f32_16x16x32_bf16 v[58:61], v[176:179], v[200:203], v[58:61]
	v_mfma_f32_16x16x32_bf16 v[46:49], v[148:151], v[208:211], v[46:49]
	v_mfma_f32_16x16x32_bf16 v[42:45], v[176:179], v[208:211], v[42:45]
	v_mfma_f32_16x16x32_bf16 v[30:33], v[148:151], v[216:219], v[30:33]
	v_mfma_f32_16x16x32_bf16 v[26:29], v[176:179], v[216:219], v[26:29]
	v_mfma_f32_16x16x32_bf16 v[14:17], v[148:151], v[224:227], v[14:17]
	v_mfma_f32_16x16x32_bf16 v[10:13], v[176:179], v[224:227], v[10:13]
	v_mfma_f32_16x16x32_bf16 v[62:65], v[156:159], v[204:207], v[62:65]
	v_mfma_f32_16x16x32_bf16 v[58:61], v[180:183], v[204:207], v[58:61]
	v_mfma_f32_16x16x32_bf16 v[46:49], v[156:159], v[212:215], v[46:49]
	v_mfma_f32_16x16x32_bf16 v[42:45], v[180:183], v[212:215], v[42:45]
	v_mfma_f32_16x16x32_bf16 v[30:33], v[156:159], v[220:223], v[30:33]
	v_mfma_f32_16x16x32_bf16 v[26:29], v[180:183], v[220:223], v[26:29]
	v_mfma_f32_16x16x32_bf16 v[14:17], v[156:159], v[228:231], v[14:17]
	v_mfma_f32_16x16x32_bf16 v[10:13], v[180:183], v[228:231], v[10:13]
	s_setprio 0
	s_setprio 1
	v_mfma_f32_16x16x32_bf16 v[54:57], v[184:187], v[200:203], v[54:57]
	v_mfma_f32_16x16x32_bf16 v[50:53], v[192:195], v[200:203], v[50:53]
	v_mfma_f32_16x16x32_bf16 v[38:41], v[184:187], v[208:211], v[38:41]
	v_mfma_f32_16x16x32_bf16 v[34:37], v[192:195], v[208:211], v[34:37]
	v_mfma_f32_16x16x32_bf16 v[22:25], v[184:187], v[216:219], v[22:25]
	v_mfma_f32_16x16x32_bf16 v[18:21], v[192:195], v[216:219], v[18:21]
	v_mfma_f32_16x16x32_bf16 v[6:9], v[184:187], v[224:227], v[6:9]
	v_mfma_f32_16x16x32_bf16 v[2:5], v[192:195], v[224:227], v[2:5]
	v_mfma_f32_16x16x32_bf16 v[54:57], v[188:191], v[204:207], v[54:57]
	v_mfma_f32_16x16x32_bf16 v[50:53], v[196:199], v[204:207], v[50:53]
	v_mfma_f32_16x16x32_bf16 v[38:41], v[188:191], v[212:215], v[38:41]
	v_mfma_f32_16x16x32_bf16 v[34:37], v[196:199], v[212:215], v[34:37]
	v_mfma_f32_16x16x32_bf16 v[22:25], v[188:191], v[220:223], v[22:25]
	v_mfma_f32_16x16x32_bf16 v[18:21], v[196:199], v[220:223], v[18:21]
	v_mfma_f32_16x16x32_bf16 v[6:9], v[188:191], v[228:231], v[6:9]
	v_mfma_f32_16x16x32_bf16 v[2:5], v[196:199], v[228:231], v[2:5]
	s_add_i32 s48, s48, 2
	s_add_u32 s4, s4, 0x100
	s_addc_u32 s5, s5, 0
	s_add_u32 s25, s25, 0x100
	s_addc_u32 s47, s47, 0
	s_cmp_gt_u32 s48, 13
	s_setprio 0
	s_barrier
	s_cbranch_scc0 .LBB0_1400
	s_and_b64 vcc, exec, s[16:17]
	s_cbranch_vccz .LBB0_1403
	s_barrier

.LBB0_1485:
	ds_read_b128 v[142:145], v194
	ds_read_b128 v[146:149], v194 offset:1024
	ds_read_b128 v[150:153], v194 offset:2048
	ds_read_b128 v[154:157], v194 offset:3072
	ds_read_b128 v[158:161], v195
	ds_read_b128 v[162:165], v195 offset:1024
	ds_read_b128 v[166:169], v195 offset:2048
	ds_read_b128 v[170:173], v195 offset:3072
	s_add_u32 s22, s20, 0xfff00080
	s_addc_u32 s23, s21, -1
	s_cmp_eq_u32 s43, 60
	s_cselect_b32 s25, s13, s23
	s_cselect_b32 s24, s39, s22
	s_cselect_b32 s23, s11, s42
	s_cselect_b32 s22, s40, s41
	v_lshl_add_u64 v[190:191], s[20:21], 0, v[134:135]
	s_add_i32 m0, s19, 0xc000
	ds_read_b128 v[174:177], v196
	ds_read_b128 v[178:181], v196 offset:1024
	ds_read_b128 v[182:185], v196 offset:2048
	ds_read_b128 v[186:189], v196 offset:3072
	ds_read_b128 v[198:201], v196 offset:4096
	ds_read_b128 v[202:205], v196 offset:5120
	ds_read_b128 v[206:209], v196 offset:6144
	ds_read_b128 v[210:213], v196 offset:7168
	global_load_lds_dwordx4 v[190:191], off
	v_lshl_add_u64 v[190:191], s[20:21], 0, v[136:137]
	s_add_i32 m0, s19, 0xe000
	s_nop 0
	global_load_lds_dwordx4 v[190:191], off
	s_waitcnt vmcnt(8)
	s_waitcnt lgkmcnt(0)
	s_barrier
	s_setprio 1
	s_waitcnt lgkmcnt(0)
	v_mfma_f32_16x16x32_bf16 v[126:129], v[142:145], v[174:177], v[126:129]
	v_mfma_f32_16x16x32_bf16 v[122:125], v[150:153], v[174:177], v[122:125]
	v_mfma_f32_16x16x32_bf16 v[114:117], v[142:145], v[182:185], v[114:117]
	v_mfma_f32_16x16x32_bf16 v[106:109], v[150:153], v[182:185], v[106:109]
	v_mfma_f32_16x16x32_bf16 v[98:101], v[142:145], v[198:201], v[98:101]
	v_mfma_f32_16x16x32_bf16 v[90:93], v[150:153], v[198:201], v[90:93]
	v_mfma_f32_16x16x32_bf16 v[82:85], v[142:145], v[206:209], v[82:85]
	v_mfma_f32_16x16x32_bf16 v[74:77], v[150:153], v[206:209], v[74:77]
	v_mfma_f32_16x16x32_bf16 v[126:129], v[146:149], v[178:181], v[126:129]
	v_mfma_f32_16x16x32_bf16 v[122:125], v[154:157], v[178:181], v[122:125]
	v_mfma_f32_16x16x32_bf16 v[114:117], v[146:149], v[186:189], v[114:117]
	v_mfma_f32_16x16x32_bf16 v[106:109], v[154:157], v[186:189], v[106:109]
	v_mfma_f32_16x16x32_bf16 v[98:101], v[146:149], v[202:205], v[98:101]
	v_mfma_f32_16x16x32_bf16 v[90:93], v[154:157], v[202:205], v[90:93]
	v_mfma_f32_16x16x32_bf16 v[82:85], v[146:149], v[210:213], v[82:85]
	v_mfma_f32_16x16x32_bf16 v[74:77], v[154:157], v[210:213], v[74:77]
	s_setprio 0
	s_setprio 1
	v_mfma_f32_16x16x32_bf16 v[118:121], v[158:161], v[174:177], v[118:121]
	v_mfma_f32_16x16x32_bf16 v[110:113], v[166:169], v[174:177], v[110:113]
	v_mfma_f32_16x16x32_bf16 v[102:105], v[158:161], v[182:185], v[102:105]
	v_mfma_f32_16x16x32_bf16 v[94:97], v[166:169], v[182:185], v[94:97]
	v_mfma_f32_16x16x32_bf16 v[86:89], v[158:161], v[198:201], v[86:89]
	v_mfma_f32_16x16x32_bf16 v[78:81], v[166:169], v[198:201], v[78:81]
	v_mfma_f32_16x16x32_bf16 v[70:73], v[158:161], v[206:209], v[70:73]
	v_mfma_f32_16x16x32_bf16 v[66:69], v[166:169], v[206:209], v[66:69]
	v_mfma_f32_16x16x32_bf16 v[118:121], v[162:165], v[178:181], v[118:121]
	v_mfma_f32_16x16x32_bf16 v[110:113], v[170:173], v[178:181], v[110:113]
	v_mfma_f32_16x16x32_bf16 v[102:105], v[162:165], v[186:189], v[102:105]
	v_mfma_f32_16x16x32_bf16 v[94:97], v[170:173], v[186:189], v[94:97]
	v_mfma_f32_16x16x32_bf16 v[86:89], v[162:165], v[202:205], v[86:89]
	v_mfma_f32_16x16x32_bf16 v[78:81], v[170:173], v[202:205], v[78:81]
	v_mfma_f32_16x16x32_bf16 v[70:73], v[162:165], v[210:213], v[70:73]
	v_mfma_f32_16x16x32_bf16 v[66:69], v[170:173], v[210:213], v[66:69]
	s_setprio 0
	s_barrier
	s_add_i32 s44, s80, s27
	v_lshl_add_u64 v[190:191], s[22:23], 0, v[130:131]
	s_mov_b32 m0, s44
	ds_read_b128 v[174:177], v196 offset:16384
	ds_read_b128 v[178:181], v196 offset:17408
	ds_read_b128 v[182:185], v196 offset:18432
	ds_read_b128 v[186:189], v196 offset:19456
	ds_read_b128 v[198:201], v196 offset:20480
	ds_read_b128 v[202:205], v196 offset:21504
	ds_read_b128 v[206:209], v196 offset:22528
	ds_read_b128 v[210:213], v196 offset:23552
	global_load_lds_dwordx4 v[190:191], off
	s_add_i32 m0, s44, 0x2000
	s_add_u32 s44, s22, 0x100000
	v_lshl_add_u64 v[214:215], s[22:23], 0, v[132:133]
	s_addc_u32 s45, s23, 0
	s_add_i32 s46, s37, s27
	global_load_lds_dwordx4 v[214:215], off
	v_lshl_add_u64 v[216:217], s[44:45], 0, v[130:131]
	s_mov_b32 m0, s46
	v_lshl_add_u64 v[218:219], s[24:25], 0, v[132:133]
	global_load_lds_dwordx4 v[216:217], off
	v_lshl_add_u64 v[216:217], s[44:45], 0, v[132:133]
	s_add_i32 m0, s46, 0x2000
	s_nop 0
	global_load_lds_dwordx4 v[216:217], off
	v_lshl_add_u64 v[216:217], s[24:25], 0, v[130:131]
	s_mov_b32 m0, s19
	s_nop 0
	global_load_lds_dwordx4 v[216:217], off
	s_mov_b32 m0, s28
	s_nop 0
	global_load_lds_dwordx4 v[218:219], off
	s_waitcnt vmcnt(8)
	s_waitcnt lgkmcnt(0)
	s_barrier
	s_setprio 1
	s_waitcnt lgkmcnt(0)
	v_mfma_f32_16x16x32_bf16 v[62:65], v[142:145], v[174:177], v[62:65]
	v_mfma_f32_16x16x32_bf16 v[58:61], v[150:153], v[174:177], v[58:61]
	v_mfma_f32_16x16x32_bf16 v[50:53], v[142:145], v[182:185], v[50:53]
	v_mfma_f32_16x16x32_bf16 v[42:45], v[150:153], v[182:185], v[42:45]
	v_mfma_f32_16x16x32_bf16 v[34:37], v[142:145], v[198:201], v[34:37]
	v_mfma_f32_16x16x32_bf16 v[26:29], v[150:153], v[198:201], v[26:29]
	v_mfma_f32_16x16x32_bf16 v[18:21], v[142:145], v[206:209], v[18:21]
	v_mfma_f32_16x16x32_bf16 v[10:13], v[150:153], v[206:209], v[10:13]
	v_mfma_f32_16x16x32_bf16 v[62:65], v[146:149], v[178:181], v[62:65]
	v_mfma_f32_16x16x32_bf16 v[58:61], v[154:157], v[178:181], v[58:61]
	v_mfma_f32_16x16x32_bf16 v[50:53], v[146:149], v[186:189], v[50:53]
	v_mfma_f32_16x16x32_bf16 v[42:45], v[154:157], v[186:189], v[42:45]
	v_mfma_f32_16x16x32_bf16 v[34:37], v[146:149], v[202:205], v[34:37]
	v_mfma_f32_16x16x32_bf16 v[26:29], v[154:157], v[202:205], v[26:29]
	v_mfma_f32_16x16x32_bf16 v[18:21], v[146:149], v[210:213], v[18:21]
	v_mfma_f32_16x16x32_bf16 v[10:13], v[154:157], v[210:213], v[10:13]
	s_setprio 0
	s_setprio 1
	v_mfma_f32_16x16x32_bf16 v[54:57], v[158:161], v[174:177], v[54:57]
	v_mfma_f32_16x16x32_bf16 v[46:49], v[166:169], v[174:177], v[46:49]
	v_mfma_f32_16x16x32_bf16 v[38:41], v[158:161], v[182:185], v[38:41]
	v_mfma_f32_16x16x32_bf16 v[30:33], v[166:169], v[182:185], v[30:33]
	v_mfma_f32_16x16x32_bf16 v[22:25], v[158:161], v[198:201], v[22:25]
	v_mfma_f32_16x16x32_bf16 v[14:17], v[166:169], v[198:201], v[14:17]
	v_mfma_f32_16x16x32_bf16 v[6:9], v[158:161], v[206:209], v[6:9]
	v_mfma_f32_16x16x32_bf16 v[2:5], v[166:169], v[206:209], v[2:5]
	v_mfma_f32_16x16x32_bf16 v[54:57], v[162:165], v[178:181], v[54:57]
	v_mfma_f32_16x16x32_bf16 v[46:49], v[170:173], v[178:181], v[46:49]
	v_mfma_f32_16x16x32_bf16 v[38:41], v[162:165], v[186:189], v[38:41]
	v_mfma_f32_16x16x32_bf16 v[30:33], v[170:173], v[186:189], v[30:33]
	v_mfma_f32_16x16x32_bf16 v[22:25], v[162:165], v[202:205], v[22:25]
	v_mfma_f32_16x16x32_bf16 v[14:17], v[170:173], v[202:205], v[14:17]
	v_mfma_f32_16x16x32_bf16 v[6:9], v[162:165], v[210:213], v[6:9]
	v_mfma_f32_16x16x32_bf16 v[2:5], v[170:173], v[210:213], v[2:5]
	s_setprio 0
	s_barrier
	s_add_i32 s44, 0, 0x18000
	s_add_i32 s45, 0, 0x1c000
	v_add_u32_e32 v154, s44, v192
	v_add_u32_e32 v170, s45, v192
	ds_read_b128 v[142:145], v154
	ds_read_b128 v[146:149], v154 offset:1024
	ds_read_b128 v[150:153], v154 offset:2048
	ds_read_b128 v[154:157], v154 offset:3072
	ds_read_b128 v[158:161], v170
	ds_read_b128 v[162:165], v170 offset:1024
	ds_read_b128 v[166:169], v170 offset:2048
	ds_read_b128 v[170:173], v170 offset:3072
	s_add_u32 s24, s24, 0x100000
	s_addc_u32 s25, s25, 0
	s_mov_b32 m0, s29
	v_lshl_add_u64 v[220:221], s[24:25], 0, v[130:131]
	ds_read_b128 v[174:177], v196 offset:32768
	ds_read_b128 v[178:181], v196 offset:33792
	ds_read_b128 v[182:185], v196 offset:34816
	ds_read_b128 v[186:189], v196 offset:35840
	ds_read_b128 v[198:201], v196 offset:36864
	ds_read_b128 v[202:205], v196 offset:37888
	ds_read_b128 v[206:209], v196 offset:38912
	ds_read_b128 v[210:213], v196 offset:39936
	global_load_lds_dwordx4 v[220:221], off
	v_lshl_add_u64 v[220:221], s[24:25], 0, v[132:133]
	s_mov_b32 m0, s30
	s_nop 0
	global_load_lds_dwordx4 v[220:221], off
	s_waitcnt vmcnt(8)
	s_waitcnt lgkmcnt(0)
	s_barrier
	s_setprio 1
	s_waitcnt lgkmcnt(0)
	v_mfma_f32_16x16x32_bf16 v[126:129], v[142:145], v[174:177], v[126:129]
	v_mfma_f32_16x16x32_bf16 v[122:125], v[150:153], v[174:177], v[122:125]
	v_mfma_f32_16x16x32_bf16 v[114:117], v[142:145], v[182:185], v[114:117]
	v_mfma_f32_16x16x32_bf16 v[106:109], v[150:153], v[182:185], v[106:109]
	v_mfma_f32_16x16x32_bf16 v[98:101], v[142:145], v[198:201], v[98:101]
	v_mfma_f32_16x16x32_bf16 v[90:93], v[150:153], v[198:201], v[90:93]
	v_mfma_f32_16x16x32_bf16 v[82:85], v[142:145], v[206:209], v[82:85]
	v_mfma_f32_16x16x32_bf16 v[74:77], v[150:153], v[206:209], v[74:77]
	v_mfma_f32_16x16x32_bf16 v[126:129], v[146:149], v[178:181], v[126:129]
	v_mfma_f32_16x16x32_bf16 v[122:125], v[154:157], v[178:181], v[122:125]
	v_mfma_f32_16x16x32_bf16 v[114:117], v[146:149], v[186:189], v[114:117]
	v_mfma_f32_16x16x32_bf16 v[106:109], v[154:157], v[186:189], v[106:109]
	v_mfma_f32_16x16x32_bf16 v[98:101], v[146:149], v[202:205], v[98:101]
	v_mfma_f32_16x16x32_bf16 v[90:93], v[154:157], v[202:205], v[90:93]
	v_mfma_f32_16x16x32_bf16 v[82:85], v[146:149], v[210:213], v[82:85]
	v_mfma_f32_16x16x32_bf16 v[74:77], v[154:157], v[210:213], v[74:77]
	s_setprio 0
	s_setprio 1
	v_mfma_f32_16x16x32_bf16 v[118:121], v[158:161], v[174:177], v[118:121]
	v_mfma_f32_16x16x32_bf16 v[110:113], v[166:169], v[174:177], v[110:113]
	v_mfma_f32_16x16x32_bf16 v[102:105], v[158:161], v[182:185], v[102:105]
	v_mfma_f32_16x16x32_bf16 v[94:97], v[166:169], v[182:185], v[94:97]
	v_mfma_f32_16x16x32_bf16 v[86:89], v[158:161], v[198:201], v[86:89]
	v_mfma_f32_16x16x32_bf16 v[78:81], v[166:169], v[198:201], v[78:81]
	v_mfma_f32_16x16x32_bf16 v[70:73], v[158:161], v[206:209], v[70:73]
	v_mfma_f32_16x16x32_bf16 v[66:69], v[166:169], v[206:209], v[66:69]
	v_mfma_f32_16x16x32_bf16 v[118:121], v[162:165], v[178:181], v[118:121]
	v_mfma_f32_16x16x32_bf16 v[110:113], v[170:173], v[178:181], v[110:113]
	v_mfma_f32_16x16x32_bf16 v[102:105], v[162:165], v[186:189], v[102:105]
	v_mfma_f32_16x16x32_bf16 v[94:97], v[170:173], v[186:189], v[94:97]
	v_mfma_f32_16x16x32_bf16 v[86:89], v[162:165], v[202:205], v[86:89]
	v_mfma_f32_16x16x32_bf16 v[78:81], v[170:173], v[202:205], v[78:81]
	v_mfma_f32_16x16x32_bf16 v[70:73], v[162:165], v[210:213], v[70:73]
	v_mfma_f32_16x16x32_bf16 v[66:69], v[170:173], v[210:213], v[66:69]
	s_setprio 0
	s_barrier
	s_add_i32 s24, s44, s27
	v_lshl_add_u64 v[190:191], v[190:191], 0, s[4:5]
	s_mov_b32 m0, s24
	ds_read_b128 v[174:177], v196 offset:49152
	ds_read_b128 v[178:181], v196 offset:50176
	ds_read_b128 v[182:185], v196 offset:51200
	ds_read_b128 v[186:189], v196 offset:52224
	ds_read_b128 v[198:201], v196 offset:53248
	ds_read_b128 v[202:205], v196 offset:54272
	ds_read_b128 v[206:209], v196 offset:55296
	ds_read_b128 v[210:213], v196 offset:56320
	global_load_lds_dwordx4 v[190:191], off
	s_add_i32 m0, s24, 0x2000
	s_add_u32 s22, s22, 0x100080
	v_lshl_add_u64 v[190:191], v[214:215], 0, s[4:5]
	s_addc_u32 s23, s23, 0
	s_add_i32 s24, s45, s27
	global_load_lds_dwordx4 v[190:191], off
	v_lshl_add_u64 v[190:191], s[22:23], 0, v[130:131]
	s_mov_b32 m0, s24
	s_nop 0
	global_load_lds_dwordx4 v[190:191], off
	v_lshl_add_u64 v[190:191], s[22:23], 0, v[132:133]
	s_add_i32 m0, s24, 0x2000
	s_nop 0
	global_load_lds_dwordx4 v[190:191], off
	v_lshl_add_u64 v[190:191], v[216:217], 0, s[4:5]
	s_mov_b32 m0, s34
	s_nop 0
	global_load_lds_dwordx4 v[190:191], off
	v_lshl_add_u64 v[190:191], v[218:219], 0, s[4:5]
	s_mov_b32 m0, s35
	s_nop 0
	global_load_lds_dwordx4 v[190:191], off
	s_waitcnt vmcnt(8)
	s_waitcnt lgkmcnt(0)
	s_barrier
	s_setprio 1
	s_waitcnt lgkmcnt(0)
	v_mfma_f32_16x16x32_bf16 v[62:65], v[142:145], v[174:177], v[62:65]
	v_mfma_f32_16x16x32_bf16 v[58:61], v[150:153], v[174:177], v[58:61]
	v_mfma_f32_16x16x32_bf16 v[50:53], v[142:145], v[182:185], v[50:53]
	v_mfma_f32_16x16x32_bf16 v[42:45], v[150:153], v[182:185], v[42:45]
	v_mfma_f32_16x16x32_bf16 v[34:37], v[142:145], v[198:201], v[34:37]
	v_mfma_f32_16x16x32_bf16 v[26:29], v[150:153], v[198:201], v[26:29]
	v_mfma_f32_16x16x32_bf16 v[18:21], v[142:145], v[206:209], v[18:21]
	v_mfma_f32_16x16x32_bf16 v[10:13], v[150:153], v[206:209], v[10:13]
	v_mfma_f32_16x16x32_bf16 v[62:65], v[146:149], v[178:181], v[62:65]
	v_mfma_f32_16x16x32_bf16 v[58:61], v[154:157], v[178:181], v[58:61]
	v_mfma_f32_16x16x32_bf16 v[50:53], v[146:149], v[186:189], v[50:53]
	v_mfma_f32_16x16x32_bf16 v[42:45], v[154:157], v[186:189], v[42:45]
	v_mfma_f32_16x16x32_bf16 v[34:37], v[146:149], v[202:205], v[34:37]
	v_mfma_f32_16x16x32_bf16 v[26:29], v[154:157], v[202:205], v[26:29]
	v_mfma_f32_16x16x32_bf16 v[18:21], v[146:149], v[210:213], v[18:21]
	v_mfma_f32_16x16x32_bf16 v[10:13], v[154:157], v[210:213], v[10:13]
	s_setprio 0
	s_setprio 1
	v_mfma_f32_16x16x32_bf16 v[54:57], v[158:161], v[174:177], v[54:57]
	v_mfma_f32_16x16x32_bf16 v[46:49], v[166:169], v[174:177], v[46:49]
	v_mfma_f32_16x16x32_bf16 v[38:41], v[158:161], v[182:185], v[38:41]
	v_mfma_f32_16x16x32_bf16 v[30:33], v[166:169], v[182:185], v[30:33]
	v_mfma_f32_16x16x32_bf16 v[22:25], v[158:161], v[198:201], v[22:25]
	v_mfma_f32_16x16x32_bf16 v[14:17], v[166:169], v[198:201], v[14:17]
	v_mfma_f32_16x16x32_bf16 v[6:9], v[158:161], v[206:209], v[6:9]
	v_mfma_f32_16x16x32_bf16 v[2:5], v[166:169], v[206:209], v[2:5]
	v_mfma_f32_16x16x32_bf16 v[54:57], v[162:165], v[178:181], v[54:57]
	v_mfma_f32_16x16x32_bf16 v[46:49], v[170:173], v[178:181], v[46:49]
	v_mfma_f32_16x16x32_bf16 v[38:41], v[162:165], v[186:189], v[38:41]
	v_mfma_f32_16x16x32_bf16 v[30:33], v[170:173], v[186:189], v[30:33]
	v_mfma_f32_16x16x32_bf16 v[22:25], v[162:165], v[202:205], v[22:25]
	v_mfma_f32_16x16x32_bf16 v[14:17], v[170:173], v[202:205], v[14:17]
	v_mfma_f32_16x16x32_bf16 v[6:9], v[162:165], v[210:213], v[6:9]
	v_mfma_f32_16x16x32_bf16 v[2:5], v[170:173], v[210:213], v[2:5]
	s_add_i32 s43, s43, 2
	s_add_u32 s20, s20, 0x100
	s_addc_u32 s21, s21, 0
	s_add_u32 s41, s41, 0x100
	s_addc_u32 s42, s42, 0
	s_cmp_gt_u32 s43, 61
	s_setprio 0
	s_barrier
	s_cbranch_scc0 .LBB0_1485
	s_and_b64 vcc, exec, s[6:7]
	s_cbranch_vccz .LBB0_1488
	s_barrier
